# attn-C K-frag double buffer + VALU spread, K swizzle bit7 conflict-free, lean relu/plain GEMM epilogues, counted waits in dilated loop
# speedup vs baseline: 1.0021x; 1.0021x over previous
;     __device__ __forceinline__ void operator()(const f32x4 (&acc)[2][2][4][2], const Unit& u, int wr, int wc, int fr, int fq) const {
;         const int row0 = u.pm * BM + wr * 64 + fr, col0 = u.pn * BM + wc * 32 + 8 * fq;
;         if (dry) return;
;     ...
; #pragma unroll
;         for (int ai = 0; ai < 2; ++ai)
; #pragma unroll
;             for (int m = 0; m < 4; ++m) {
;                 const int row = row0 + ai * HALF + m * 16;
;                 bf16_t* rowp = O + (size_t)row * ldc + col0;
;                 f32x4 cs0 = {1.f, 0.f, 1.f, 0.f}, cs1 = {1.f, 0.f, 1.f, 0.f};
;                 if (mode == 1) {
.LBB0_121:
	s_andn2_b64 vcc, exec, s[54:55]
	s_cbranch_vccnz .LBB0_256
	s_lshl_b32 s66, s89, 8
	v_add_u32_e32 v209, s66, v180
	v_lshl_or_b32 v146, s57, 8, v207
	s_cmp_eq_u32 s60, 2
	s_cbranch_scc1 .Lmy_epi_relu
	s_cmp_eq_u32 s60, 0
	s_cbranch_scc1 .Lmy_epi_plain
	s_andn2_b64 vcc, exec, s[34:35]
	s_mov_b64 s[8:9], -1
	s_cbranch_vccnz .LBB0_252
	s_and_b64 vcc, exec, s[30:31]
	s_cbranch_vccz .LBB0_125
	v_ashrrev_i32_e32 v96, s10, v209
	v_and_b32_e32 v130, s28, v209
	v_and_b32_e32 v96, s88, v96
	v_lshl_add_u32 v96, v130, s53, v96
	v_lshlrev_b64 v[130:131], 8, v[96:97]
	v_lshl_add_u64 v[130:131], v[162:163], 0, v[130:131]
	global_load_dwordx4 v[134:137], v[130:131], off
	s_nop 0
	global_load_dwordx4 v[130:133], v[130:131], off offset:16
	s_cmp_lt_i32 s60, 2
	s_cbranch_scc1 .LBB0_129
	s_branch .LBB0_126

; __device__ __forceinline__ unsigned cvt_pk_bf16(float lo, float hi) { unsigned r; asm volatile("v_cvt_pk_bf16_f32 %0, %1, %2" : "=v"(r) : "v"(lo), "v"(hi)); return r; }
;     __device__ __forceinline__ void operator()(const f32x4 (&acc)[2][2][4][2], const Unit& u, int wr, int wc, int fr, int fq) const {
;     ...
;             for (int m = 0; m < 4; ++m) {
;                 const int row = row0 + ai * HALF + m * 16;
;                 bf16_t* rowp = O + (size_t)row * ldc + col0;
;                 f32x4 cs0 = {1.f, 0.f, 1.f, 0.f}, cs1 = {1.f, 0.f, 1.f, 0.f};
;                 if (mode == 1) {
;                     const int L1 = (1 << log2L) - 1, line = row >> log2L, uu = row & L1, rho = line & ((1 << log2d) - 1), pos = (uu << log2d) + rho;
;                     const float* tp = rope + ((size_t)pos * 32 + (wc & 1) * 16 + 4 * fq) * 2;
;                     cs0 = *(const f32x4*)tp; cs1 = *(const f32x4*)(tp + 4);
;                 }
; #pragma unroll
;                 for (int bj = 0; bj < 2; ++bj) {
;                     f32x4 v0 = acc[ai][bj][m][0], v1 = acc[ai][bj][m][1];
;                     if (mode == 2) {
; #pragma unroll
;                         for (int e = 0; e < 4; ++e) { float a = fmaxf(v0[e], 0.f), b = fmaxf(v1[e], 0.f); v0[e] = a * a; v1[e] = b * b; }
;                     } else if (mode == 1) {
;                         f32x4 r0, r1;
;                         r0[0] = v0[0] * cs0[0] - v0[1] * cs0[1]; r0[1] = v0[0] * cs0[1] + v0[1] * cs0[0];
;                         r0[2] = v0[2] * cs0[2] - v0[3] * cs0[3]; r0[3] = v0[2] * cs0[3] + v0[3] * cs0[2];
;                         r1[0] = v1[0] * cs1[0] - v1[1] * cs1[1]; r1[1] = v1[0] * cs1[1] + v1[1] * cs1[0];
;                         r1[2] = v1[2] * cs1[2] - v1[3] * cs1[3]; r1[3] = v1[2] * cs1[3] + v1[3] * cs1[2];
;                         v0 = r0; v1 = r1;
;                     }
;                     u32x4 w; w.x = cvt_pk_bf16(v0[0], v0[1]); w.y = cvt_pk_bf16(v0[2], v0[3]); w.z = cvt_pk_bf16(v1[0], v1[1]); w.w = cvt_pk_bf16(v1[2], v1[3]);
;                     *(u32x4*)(rowp + bj * HALF) = w;
.LBB0_139:
	v_cndmask_b32_e64 v96, 0, 1, s[30:31]
	v_cvt_pk_bf16_f32 v130, v140, v141
	v_cvt_pk_bf16_f32 v131, v142, v152
	v_cvt_pk_bf16_f32 v132, v144, v145
	v_cvt_pk_bf16_f32 v133, v148, v150
	global_store_dwordx4 v[138:139], v[130:133], off offset:256
	v_cmp_ne_u32_e64 s[8:9], 1, v96
	s_andn2_b64 vcc, exec, s[30:31]
	v_or_b32_e32 v138, 16, v209
	s_cbranch_vccnz .LBB0_141
	v_ashrrev_i32_e32 v96, s10, v138
	v_and_b32_e32 v130, s28, v138
	v_and_b32_e32 v96, s88, v96
	v_lshl_add_u32 v96, v130, s53, v96
	v_lshlrev_b64 v[130:131], 8, v[96:97]
	v_lshl_add_u64 v[130:131], v[162:163], 0, v[130:131]
	global_load_dwordx4 v[134:137], v[130:131], off
	s_nop 0
	global_load_dwordx4 v[130:133], v[130:131], off offset:16
	s_cmp_lt_i32 s60, 2
	s_mov_b64 s[64:65], -1
	s_cbranch_scc1 .LBB0_145
	s_branch .LBB0_142

; __device__ __forceinline__ unsigned cvt_pk_bf16(float lo, float hi) { unsigned r; asm volatile("v_cvt_pk_bf16_f32 %0, %1, %2" : "=v"(r) : "v"(lo), "v"(hi)); return r; }
;     __device__ __forceinline__ void operator()(const f32x4 (&acc)[2][2][4][2], const Unit& u, int wr, int wc, int fr, int fq) const {
;     ...
;             for (int m = 0; m < 4; ++m) {
;                 const int row = row0 + ai * HALF + m * 16;
;                 bf16_t* rowp = O + (size_t)row * ldc + col0;
;                 f32x4 cs0 = {1.f, 0.f, 1.f, 0.f}, cs1 = {1.f, 0.f, 1.f, 0.f};
;                 if (mode == 1) {
;                     const int L1 = (1 << log2L) - 1, line = row >> log2L, uu = row & L1, rho = line & ((1 << log2d) - 1), pos = (uu << log2d) + rho;
;                     const float* tp = rope + ((size_t)pos * 32 + (wc & 1) * 16 + 4 * fq) * 2;
;                     cs0 = *(const f32x4*)tp; cs1 = *(const f32x4*)(tp + 4);
;                 }
; #pragma unroll
;                 for (int bj = 0; bj < 2; ++bj) {
;                     f32x4 v0 = acc[ai][bj][m][0], v1 = acc[ai][bj][m][1];
;                     if (mode == 2) {
; #pragma unroll
;                         for (int e = 0; e < 4; ++e) { float a = fmaxf(v0[e], 0.f), b = fmaxf(v1[e], 0.f); v0[e] = a * a; v1[e] = b * b; }
;                     } else if (mode == 1) {
;                         f32x4 r0, r1;
;                         r0[0] = v0[0] * cs0[0] - v0[1] * cs0[1]; r0[1] = v0[0] * cs0[1] + v0[1] * cs0[0];
;                         r0[2] = v0[2] * cs0[2] - v0[3] * cs0[3]; r0[3] = v0[2] * cs0[3] + v0[3] * cs0[2];
;                         r1[0] = v1[0] * cs1[0] - v1[1] * cs1[1]; r1[1] = v1[0] * cs1[1] + v1[1] * cs1[0];
;                         r1[2] = v1[2] * cs1[2] - v1[3] * cs1[3]; r1[3] = v1[2] * cs1[3] + v1[3] * cs1[2];
;                         v0 = r0; v1 = r1;
;                     }
;                     u32x4 w; w.x = cvt_pk_bf16(v0[0], v0[1]); w.y = cvt_pk_bf16(v0[2], v0[3]); w.z = cvt_pk_bf16(v1[0], v1[1]); w.w = cvt_pk_bf16(v1[2], v1[3]);
;                     *(u32x4*)(rowp + bj * HALF) = w;
.LBB0_155:
	v_cvt_pk_bf16_f32 v130, v140, v141
	v_cvt_pk_bf16_f32 v131, v142, v152
	v_cvt_pk_bf16_f32 v132, v144, v145
	v_cvt_pk_bf16_f32 v133, v148, v150
	global_store_dwordx4 v[138:139], v[130:133], off offset:256
	s_and_b64 vcc, exec, s[8:9]
	v_or_b32_e32 v138, 32, v209
	s_cbranch_vccnz .LBB0_157
	v_ashrrev_i32_e32 v96, s10, v138
	v_and_b32_e32 v130, s28, v138
	v_and_b32_e32 v96, s88, v96
	v_lshl_add_u32 v96, v130, s53, v96
	v_lshlrev_b64 v[130:131], 8, v[96:97]
	v_lshl_add_u64 v[130:131], v[162:163], 0, v[130:131]
	global_load_dwordx4 v[134:137], v[130:131], off
	s_nop 0
	global_load_dwordx4 v[130:133], v[130:131], off offset:16
	s_cmp_lt_i32 s60, 2
	s_mov_b64 s[64:65], -1
	s_cbranch_scc1 .LBB0_161
	s_branch .LBB0_158

; __device__ __forceinline__ unsigned cvt_pk_bf16(float lo, float hi) { unsigned r; asm volatile("v_cvt_pk_bf16_f32 %0, %1, %2" : "=v"(r) : "v"(lo), "v"(hi)); return r; }
;     __device__ __forceinline__ void operator()(const f32x4 (&acc)[2][2][4][2], const Unit& u, int wr, int wc, int fr, int fq) const {
;     ...
;             for (int m = 0; m < 4; ++m) {
;                 const int row = row0 + ai * HALF + m * 16;
;                 bf16_t* rowp = O + (size_t)row * ldc + col0;
;                 f32x4 cs0 = {1.f, 0.f, 1.f, 0.f}, cs1 = {1.f, 0.f, 1.f, 0.f};
;                 if (mode == 1) {
;                     const int L1 = (1 << log2L) - 1, line = row >> log2L, uu = row & L1, rho = line & ((1 << log2d) - 1), pos = (uu << log2d) + rho;
;                     const float* tp = rope + ((size_t)pos * 32 + (wc & 1) * 16 + 4 * fq) * 2;
;                     cs0 = *(const f32x4*)tp; cs1 = *(const f32x4*)(tp + 4);
;                 }
; #pragma unroll
;                 for (int bj = 0; bj < 2; ++bj) {
;                     f32x4 v0 = acc[ai][bj][m][0], v1 = acc[ai][bj][m][1];
;                     if (mode == 2) {
; #pragma unroll
;                         for (int e = 0; e < 4; ++e) { float a = fmaxf(v0[e], 0.f), b = fmaxf(v1[e], 0.f); v0[e] = a * a; v1[e] = b * b; }
;                     } else if (mode == 1) {
;                         f32x4 r0, r1;
;                         r0[0] = v0[0] * cs0[0] - v0[1] * cs0[1]; r0[1] = v0[0] * cs0[1] + v0[1] * cs0[0];
;                         r0[2] = v0[2] * cs0[2] - v0[3] * cs0[3]; r0[3] = v0[2] * cs0[3] + v0[3] * cs0[2];
;                         r1[0] = v1[0] * cs1[0] - v1[1] * cs1[1]; r1[1] = v1[0] * cs1[1] + v1[1] * cs1[0];
;                         r1[2] = v1[2] * cs1[2] - v1[3] * cs1[3]; r1[3] = v1[2] * cs1[3] + v1[3] * cs1[2];
;                         v0 = r0; v1 = r1;
;                     }
;                     u32x4 w; w.x = cvt_pk_bf16(v0[0], v0[1]); w.y = cvt_pk_bf16(v0[2], v0[3]); w.z = cvt_pk_bf16(v1[0], v1[1]); w.w = cvt_pk_bf16(v1[2], v1[3]);
;                     *(u32x4*)(rowp + bj * HALF) = w;
.LBB0_171:
	v_cvt_pk_bf16_f32 v130, v140, v141
	v_cvt_pk_bf16_f32 v131, v142, v152
	v_cvt_pk_bf16_f32 v132, v144, v145
	v_cvt_pk_bf16_f32 v133, v148, v150
	global_store_dwordx4 v[138:139], v[130:133], off offset:256
	s_and_b64 vcc, exec, s[8:9]
	v_or_b32_e32 v138, 48, v209
	s_cbranch_vccnz .LBB0_173
	v_ashrrev_i32_e32 v96, s10, v138
	v_and_b32_e32 v130, s28, v138
	v_and_b32_e32 v96, s88, v96
	v_lshl_add_u32 v96, v130, s53, v96
	v_lshlrev_b64 v[130:131], 8, v[96:97]
	v_lshl_add_u64 v[130:131], v[162:163], 0, v[130:131]
	global_load_dwordx4 v[134:137], v[130:131], off
	s_nop 0
	global_load_dwordx4 v[130:133], v[130:131], off offset:16
	s_cmp_lt_i32 s60, 2
	s_mov_b64 s[64:65], -1
	s_cbranch_scc1 .LBB0_177
	s_branch .LBB0_174

; __device__ __forceinline__ unsigned cvt_pk_bf16(float lo, float hi) { unsigned r; asm volatile("v_cvt_pk_bf16_f32 %0, %1, %2" : "=v"(r) : "v"(lo), "v"(hi)); return r; }
;     __device__ __forceinline__ void operator()(const f32x4 (&acc)[2][2][4][2], const Unit& u, int wr, int wc, int fr, int fq) const {
;     ...
;             for (int m = 0; m < 4; ++m) {
;                 const int row = row0 + ai * HALF + m * 16;
;                 bf16_t* rowp = O + (size_t)row * ldc + col0;
;                 f32x4 cs0 = {1.f, 0.f, 1.f, 0.f}, cs1 = {1.f, 0.f, 1.f, 0.f};
;                 if (mode == 1) {
;                     const int L1 = (1 << log2L) - 1, line = row >> log2L, uu = row & L1, rho = line & ((1 << log2d) - 1), pos = (uu << log2d) + rho;
;                     const float* tp = rope + ((size_t)pos * 32 + (wc & 1) * 16 + 4 * fq) * 2;
;                     cs0 = *(const f32x4*)tp; cs1 = *(const f32x4*)(tp + 4);
;                 }
; #pragma unroll
;                 for (int bj = 0; bj < 2; ++bj) {
;                     f32x4 v0 = acc[ai][bj][m][0], v1 = acc[ai][bj][m][1];
;                     if (mode == 2) {
; #pragma unroll
;                         for (int e = 0; e < 4; ++e) { float a = fmaxf(v0[e], 0.f), b = fmaxf(v1[e], 0.f); v0[e] = a * a; v1[e] = b * b; }
;                     } else if (mode == 1) {
;                         f32x4 r0, r1;
;                         r0[0] = v0[0] * cs0[0] - v0[1] * cs0[1]; r0[1] = v0[0] * cs0[1] + v0[1] * cs0[0];
;                         r0[2] = v0[2] * cs0[2] - v0[3] * cs0[3]; r0[3] = v0[2] * cs0[3] + v0[3] * cs0[2];
;                         r1[0] = v1[0] * cs1[0] - v1[1] * cs1[1]; r1[1] = v1[0] * cs1[1] + v1[1] * cs1[0];
;                         r1[2] = v1[2] * cs1[2] - v1[3] * cs1[3]; r1[3] = v1[2] * cs1[3] + v1[3] * cs1[2];
;                         v0 = r0; v1 = r1;
;                     }
;                     u32x4 w; w.x = cvt_pk_bf16(v0[0], v0[1]); w.y = cvt_pk_bf16(v0[2], v0[3]); w.z = cvt_pk_bf16(v1[0], v1[1]); w.w = cvt_pk_bf16(v1[2], v1[3]);
;                     *(u32x4*)(rowp + bj * HALF) = w;
.LBB0_187:
	v_cvt_pk_bf16_f32 v130, v140, v141
	v_cvt_pk_bf16_f32 v131, v142, v152
	v_cvt_pk_bf16_f32 v132, v144, v145
	v_cvt_pk_bf16_f32 v133, v148, v150
	global_store_dwordx4 v[138:139], v[130:133], off offset:256
	s_and_b64 vcc, exec, s[8:9]
	v_add_u32_e32 v138, 0x80, v209
	s_cbranch_vccnz .LBB0_189
	v_ashrrev_i32_e32 v96, s10, v138
	v_and_b32_e32 v130, s28, v138
	v_and_b32_e32 v96, s88, v96
	v_lshl_add_u32 v96, v130, s53, v96
	v_lshlrev_b64 v[130:131], 8, v[96:97]
	v_lshl_add_u64 v[130:131], v[162:163], 0, v[130:131]
	global_load_dwordx4 v[134:137], v[130:131], off
	s_nop 0
	global_load_dwordx4 v[130:133], v[130:131], off offset:16
	s_cmp_lt_i32 s60, 2
	s_mov_b64 s[64:65], -1
	s_cbranch_scc1 .LBB0_193
	s_branch .LBB0_190

; __device__ __forceinline__ unsigned cvt_pk_bf16(float lo, float hi) { unsigned r; asm volatile("v_cvt_pk_bf16_f32 %0, %1, %2" : "=v"(r) : "v"(lo), "v"(hi)); return r; }
;     __device__ __forceinline__ void operator()(const f32x4 (&acc)[2][2][4][2], const Unit& u, int wr, int wc, int fr, int fq) const {
;     ...
;             for (int m = 0; m < 4; ++m) {
;                 const int row = row0 + ai * HALF + m * 16;
;                 bf16_t* rowp = O + (size_t)row * ldc + col0;
;                 f32x4 cs0 = {1.f, 0.f, 1.f, 0.f}, cs1 = {1.f, 0.f, 1.f, 0.f};
;                 if (mode == 1) {
;                     const int L1 = (1 << log2L) - 1, line = row >> log2L, uu = row & L1, rho = line & ((1 << log2d) - 1), pos = (uu << log2d) + rho;
;                     const float* tp = rope + ((size_t)pos * 32 + (wc & 1) * 16 + 4 * fq) * 2;
;                     cs0 = *(const f32x4*)tp; cs1 = *(const f32x4*)(tp + 4);
;                 }
; #pragma unroll
;                 for (int bj = 0; bj < 2; ++bj) {
;                     f32x4 v0 = acc[ai][bj][m][0], v1 = acc[ai][bj][m][1];
;                     if (mode == 2) {
; #pragma unroll
;                         for (int e = 0; e < 4; ++e) { float a = fmaxf(v0[e], 0.f), b = fmaxf(v1[e], 0.f); v0[e] = a * a; v1[e] = b * b; }
;                     } else if (mode == 1) {
;                         f32x4 r0, r1;
;                         r0[0] = v0[0] * cs0[0] - v0[1] * cs0[1]; r0[1] = v0[0] * cs0[1] + v0[1] * cs0[0];
;                         r0[2] = v0[2] * cs0[2] - v0[3] * cs0[3]; r0[3] = v0[2] * cs0[3] + v0[3] * cs0[2];
;                         r1[0] = v1[0] * cs1[0] - v1[1] * cs1[1]; r1[1] = v1[0] * cs1[1] + v1[1] * cs1[0];
;                         r1[2] = v1[2] * cs1[2] - v1[3] * cs1[3]; r1[3] = v1[2] * cs1[3] + v1[3] * cs1[2];
;                         v0 = r0; v1 = r1;
;                     }
;                     u32x4 w; w.x = cvt_pk_bf16(v0[0], v0[1]); w.y = cvt_pk_bf16(v0[2], v0[3]); w.z = cvt_pk_bf16(v1[0], v1[1]); w.w = cvt_pk_bf16(v1[2], v1[3]);
;                     *(u32x4*)(rowp + bj * HALF) = w;
.LBB0_203:
	v_cvt_pk_bf16_f32 v130, v140, v141
	v_cvt_pk_bf16_f32 v131, v142, v152
	v_cvt_pk_bf16_f32 v132, v144, v145
	v_cvt_pk_bf16_f32 v133, v148, v150
	global_store_dwordx4 v[138:139], v[130:133], off offset:256
	s_and_b64 vcc, exec, s[8:9]
	v_add_u32_e32 v138, 0x90, v209
	s_cbranch_vccnz .LBB0_205
	v_ashrrev_i32_e32 v96, s10, v138
	v_and_b32_e32 v130, s28, v138
	v_and_b32_e32 v96, s88, v96
	v_lshl_add_u32 v96, v130, s53, v96
	v_lshlrev_b64 v[130:131], 8, v[96:97]
	v_lshl_add_u64 v[130:131], v[162:163], 0, v[130:131]
	global_load_dwordx4 v[134:137], v[130:131], off
	s_nop 0
	global_load_dwordx4 v[130:133], v[130:131], off offset:16
	s_cmp_lt_i32 s60, 2
	s_mov_b64 s[64:65], -1
	s_cbranch_scc1 .LBB0_209
	s_branch .LBB0_206

; __device__ __forceinline__ unsigned cvt_pk_bf16(float lo, float hi) { unsigned r; asm volatile("v_cvt_pk_bf16_f32 %0, %1, %2" : "=v"(r) : "v"(lo), "v"(hi)); return r; }
;     __device__ __forceinline__ void operator()(const f32x4 (&acc)[2][2][4][2], const Unit& u, int wr, int wc, int fr, int fq) const {
;     ...
;             for (int m = 0; m < 4; ++m) {
;                 const int row = row0 + ai * HALF + m * 16;
;                 bf16_t* rowp = O + (size_t)row * ldc + col0;
;                 f32x4 cs0 = {1.f, 0.f, 1.f, 0.f}, cs1 = {1.f, 0.f, 1.f, 0.f};
;                 if (mode == 1) {
;                     const int L1 = (1 << log2L) - 1, line = row >> log2L, uu = row & L1, rho = line & ((1 << log2d) - 1), pos = (uu << log2d) + rho;
;                     const float* tp = rope + ((size_t)pos * 32 + (wc & 1) * 16 + 4 * fq) * 2;
;                     cs0 = *(const f32x4*)tp; cs1 = *(const f32x4*)(tp + 4);
;                 }
; #pragma unroll
;                 for (int bj = 0; bj < 2; ++bj) {
;                     f32x4 v0 = acc[ai][bj][m][0], v1 = acc[ai][bj][m][1];
;                     if (mode == 2) {
; #pragma unroll
;                         for (int e = 0; e < 4; ++e) { float a = fmaxf(v0[e], 0.f), b = fmaxf(v1[e], 0.f); v0[e] = a * a; v1[e] = b * b; }
;                     } else if (mode == 1) {
;                         f32x4 r0, r1;
;                         r0[0] = v0[0] * cs0[0] - v0[1] * cs0[1]; r0[1] = v0[0] * cs0[1] + v0[1] * cs0[0];
;                         r0[2] = v0[2] * cs0[2] - v0[3] * cs0[3]; r0[3] = v0[2] * cs0[3] + v0[3] * cs0[2];
;                         r1[0] = v1[0] * cs1[0] - v1[1] * cs1[1]; r1[1] = v1[0] * cs1[1] + v1[1] * cs1[0];
;                         r1[2] = v1[2] * cs1[2] - v1[3] * cs1[3]; r1[3] = v1[2] * cs1[3] + v1[3] * cs1[2];
;                         v0 = r0; v1 = r1;
;                     }
;                     u32x4 w; w.x = cvt_pk_bf16(v0[0], v0[1]); w.y = cvt_pk_bf16(v0[2], v0[3]); w.z = cvt_pk_bf16(v1[0], v1[1]); w.w = cvt_pk_bf16(v1[2], v1[3]);
;                     *(u32x4*)(rowp + bj * HALF) = w;
.LBB0_219:
	v_cvt_pk_bf16_f32 v130, v140, v141
	v_cvt_pk_bf16_f32 v131, v142, v152
	v_cvt_pk_bf16_f32 v132, v144, v145
	v_cvt_pk_bf16_f32 v133, v148, v150
	global_store_dwordx4 v[138:139], v[130:133], off offset:256
	s_and_b64 vcc, exec, s[8:9]
	v_add_u32_e32 v138, 0xa0, v209
	s_cbranch_vccnz .LBB0_221
	v_ashrrev_i32_e32 v96, s10, v138
	v_and_b32_e32 v130, s28, v138
	v_and_b32_e32 v96, s88, v96
	v_lshl_add_u32 v96, v130, s53, v96
	v_lshlrev_b64 v[130:131], 8, v[96:97]
	v_lshl_add_u64 v[130:131], v[162:163], 0, v[130:131]
	global_load_dwordx4 v[134:137], v[130:131], off
	s_nop 0
	global_load_dwordx4 v[130:133], v[130:131], off offset:16
	s_cmp_lt_i32 s60, 2
	s_mov_b64 s[64:65], -1
	s_cbranch_scc1 .LBB0_225
	s_branch .LBB0_222

; __device__ __forceinline__ unsigned cvt_pk_bf16(float lo, float hi) { unsigned r; asm volatile("v_cvt_pk_bf16_f32 %0, %1, %2" : "=v"(r) : "v"(lo), "v"(hi)); return r; }
;     __device__ __forceinline__ void operator()(const f32x4 (&acc)[2][2][4][2], const Unit& u, int wr, int wc, int fr, int fq) const {
;     ...
;             for (int m = 0; m < 4; ++m) {
;                 const int row = row0 + ai * HALF + m * 16;
;                 bf16_t* rowp = O + (size_t)row * ldc + col0;
;                 f32x4 cs0 = {1.f, 0.f, 1.f, 0.f}, cs1 = {1.f, 0.f, 1.f, 0.f};
;                 if (mode == 1) {
;                     const int L1 = (1 << log2L) - 1, line = row >> log2L, uu = row & L1, rho = line & ((1 << log2d) - 1), pos = (uu << log2d) + rho;
;                     const float* tp = rope + ((size_t)pos * 32 + (wc & 1) * 16 + 4 * fq) * 2;
;                     cs0 = *(const f32x4*)tp; cs1 = *(const f32x4*)(tp + 4);
;                 }
; #pragma unroll
;                 for (int bj = 0; bj < 2; ++bj) {
;                     f32x4 v0 = acc[ai][bj][m][0], v1 = acc[ai][bj][m][1];
;                     if (mode == 2) {
; #pragma unroll
;                         for (int e = 0; e < 4; ++e) { float a = fmaxf(v0[e], 0.f), b = fmaxf(v1[e], 0.f); v0[e] = a * a; v1[e] = b * b; }
;                     } else if (mode == 1) {
;                         f32x4 r0, r1;
;                         r0[0] = v0[0] * cs0[0] - v0[1] * cs0[1]; r0[1] = v0[0] * cs0[1] + v0[1] * cs0[0];
;                         r0[2] = v0[2] * cs0[2] - v0[3] * cs0[3]; r0[3] = v0[2] * cs0[3] + v0[3] * cs0[2];
;                         r1[0] = v1[0] * cs1[0] - v1[1] * cs1[1]; r1[1] = v1[0] * cs1[1] + v1[1] * cs1[0];
;                         r1[2] = v1[2] * cs1[2] - v1[3] * cs1[3]; r1[3] = v1[2] * cs1[3] + v1[3] * cs1[2];
;                         v0 = r0; v1 = r1;
;                     }
;                     u32x4 w; w.x = cvt_pk_bf16(v0[0], v0[1]); w.y = cvt_pk_bf16(v0[2], v0[3]); w.z = cvt_pk_bf16(v1[0], v1[1]); w.w = cvt_pk_bf16(v1[2], v1[3]);
;                     *(u32x4*)(rowp + bj * HALF) = w;
.LBB0_235:
	v_cvt_pk_bf16_f32 v130, v140, v141
	v_cvt_pk_bf16_f32 v131, v142, v152
	v_cvt_pk_bf16_f32 v132, v144, v145
	v_cvt_pk_bf16_f32 v133, v148, v150
	global_store_dwordx4 v[138:139], v[130:133], off offset:256
	s_and_b64 vcc, exec, s[8:9]
	v_add_u32_e32 v138, 0xb0, v209
	s_cbranch_vccnz .LBB0_237
	v_ashrrev_i32_e32 v96, s10, v138
	v_and_b32_e32 v130, s28, v138
	v_and_b32_e32 v96, s88, v96
	v_lshl_add_u32 v96, v130, s53, v96
	v_lshlrev_b64 v[130:131], 8, v[96:97]
	v_lshl_add_u64 v[130:131], v[162:163], 0, v[130:131]
	global_load_dwordx4 v[134:137], v[130:131], off
	s_nop 0
	global_load_dwordx4 v[130:133], v[130:131], off offset:16
	s_cmp_lt_i32 s60, 2
	s_mov_b64 s[8:9], -1
	s_cbranch_scc1 .LBB0_241
	s_branch .LBB0_238

; __device__ __forceinline__ unsigned cvt_pk_bf16(float lo, float hi) { unsigned r; asm volatile("v_cvt_pk_bf16_f32 %0, %1, %2" : "=v"(r) : "v"(lo), "v"(hi)); return r; }
;     __device__ __forceinline__ void operator()(const f32x4 (&acc)[2][2][4][2], const Unit& u, int wr, int wc, int fr, int fq) const {
;     ...
;                 for (int bj = 0; bj < 2; ++bj) {
;                     f32x4 v0 = acc[ai][bj][m][0], v1 = acc[ai][bj][m][1];
;                     if (mode == 2) {
; #pragma unroll
;                         for (int e = 0; e < 4; ++e) { float a = fmaxf(v0[e], 0.f), b = fmaxf(v1[e], 0.f); v0[e] = a * a; v1[e] = b * b; }
;                     } else if (mode == 1) {
;                         f32x4 r0, r1;
;                         r0[0] = v0[0] * cs0[0] - v0[1] * cs0[1]; r0[1] = v0[0] * cs0[1] + v0[1] * cs0[0];
;                         r0[2] = v0[2] * cs0[2] - v0[3] * cs0[3]; r0[3] = v0[2] * cs0[3] + v0[3] * cs0[2];
;                         r1[0] = v1[0] * cs1[0] - v1[1] * cs1[1]; r1[1] = v1[0] * cs1[1] + v1[1] * cs1[0];
;                         r1[2] = v1[2] * cs1[2] - v1[3] * cs1[3]; r1[3] = v1[2] * cs1[3] + v1[3] * cs1[2];
;                         v0 = r0; v1 = r1;
;                     }
;                     u32x4 w; w.x = cvt_pk_bf16(v0[0], v0[1]); w.y = cvt_pk_bf16(v0[2], v0[3]); w.z = cvt_pk_bf16(v1[0], v1[1]); w.w = cvt_pk_bf16(v1[2], v1[3]);
;                     *(u32x4*)(rowp + bj * HALF) = w;
.LBB0_251:
	s_mov_b64 s[8:9], 0
	v_cvt_pk_bf16_f32 v130, v140, v141
	v_cvt_pk_bf16_f32 v131, v144, v152
	v_cvt_pk_bf16_f32 v132, v142, v143
	v_cvt_pk_bf16_f32 v133, v148, v150
	global_store_dwordx4 v[138:139], v[130:133], off offset:256

; __device__ __forceinline__ unsigned cvt_pk_bf16(float lo, float hi) { unsigned r; asm volatile("v_cvt_pk_bf16_f32 %0, %1, %2" : "=v"(r) : "v"(lo), "v"(hi)); return r; }
; __device__ __forceinline__ float bf_lo(unsigned w) { return __uint_as_float(w << 16); }
; __device__ __forceinline__ float bf_hi(unsigned w) { return __uint_as_float(w & 0xffff0000u); }
;     __device__ __forceinline__ void operator()(const f32x4 (&acc)[2][2][4][2], const Unit& u, int wr, int wc, int fr, int fq) const {
;     ...
;             } else {
; #pragma unroll
;                 for (int ai = 0; ai < 2; ++ai) {
;                     u32x4 bb[4][2];
; #pragma unroll
;                     for (int m = 0; m < 4; ++m) { const bf16_t* bp = baseb + (size_t)(row_off + row0 + ai * HALF + m * 16) * DM + col0;
; #pragma unroll
;                         for (int bj = 0; bj < 2; ++bj) bb[m][bj] = *(const u32x4*)(bp + bj * HALF); }
;                     __builtin_amdgcn_sched_barrier(0);
; #pragma unroll
;                     for (int m = 0; m < 4; ++m) { bf16_t* op = outb + (size_t)(row_off + row0 + ai * HALF + m * 16) * DM + col0;
; #pragma unroll
;                         for (int bj = 0; bj < 2; ++bj) { const u32x4 ub = bb[m][bj];
;                             const f32x4 b0 = {bf_lo(ub.x), bf_hi(ub.x), bf_lo(ub.y), bf_hi(ub.y)}, b1 = {bf_lo(ub.z), bf_hi(ub.z), bf_lo(ub.w), bf_hi(ub.w)};
;                             const f32x4 v0 = b0 + gt[bj][0] * acc[ai][bj][m][0], v1 = b1 + gt[bj][1] * acc[ai][bj][m][1];
;                             u32x4 w; w.x = cvt_pk_bf16(v0[0], v0[1]); w.y = cvt_pk_bf16(v0[2], v0[3]); w.z = cvt_pk_bf16(v1[0], v1[1]); w.w = cvt_pk_bf16(v1[2], v1[3]);
;                             *(u32x4*)(op + bj * HALF) = w; } }
;                     __builtin_amdgcn_sched_barrier(0);
;                 }
;             }
.LBB0_255:
	v_readlane_b32 s64, v255, 21
	v_readlane_b32 s65, v255, 22
	v_lshlrev_b64 v[234:235], 11, v[148:149]
	v_readlane_b32 s66, v255, 23
	v_lshl_add_u64 v[178:179], s[64:65], 0, v[168:169]
	v_lshl_add_u64 v[146:147], v[178:179], 0, v[234:235]
	global_load_dwordx4 v[210:213], v[146:147], off
	global_load_dwordx4 v[214:217], v[146:147], off offset:256
	v_or_b32_e32 v146, 16, v148
	v_ashrrev_i32_e32 v147, 31, v146
	v_lshlrev_b64 v[146:147], 11, v[146:147]
	v_lshl_add_u64 v[146:147], v[178:179], 0, v[146:147]
	global_load_dwordx4 v[218:221], v[146:147], off
	global_load_dwordx4 v[222:225], v[146:147], off offset:256
	v_or_b32_e32 v146, 32, v148
	v_ashrrev_i32_e32 v147, 31, v146
	v_lshlrev_b64 v[146:147], 11, v[146:147]
	v_lshl_add_u64 v[146:147], v[178:179], 0, v[146:147]
	global_load_dwordx4 v[226:229], v[146:147], off
	global_load_dwordx4 v[230:233], v[146:147], off offset:256
	v_or_b32_e32 v146, 48, v148
	v_ashrrev_i32_e32 v147, 31, v146
	v_lshlrev_b64 v[146:147], 11, v[146:147]
	v_lshl_add_u64 v[146:147], v[178:179], 0, v[146:147]
	global_load_dwordx4 v[150:153], v[146:147], off
	s_nop 0
	global_load_dwordx4 v[146:149], v[146:147], off offset:256
	v_readlane_b32 s67, v255, 24
	v_lshl_add_u64 v[234:235], s[94:95], 0, v[234:235]
	s_waitcnt vmcnt(0)
	v_lshlrev_b32_e32 v236, 16, v210
	v_and_b32_e32 v237, 0xffff0000, v210
	v_lshlrev_b32_e32 v210, 16, v211
	v_and_b32_e32 v211, 0xffff0000, v211
	v_lshlrev_b32_e32 v238, 16, v212
	v_and_b32_e32 v239, 0xffff0000, v212
	v_lshlrev_b32_e32 v212, 16, v213
	v_and_b32_e32 v213, 0xffff0000, v213
	v_lshl_add_u64 v[234:235], v[234:235], 0, v[168:169]
	v_pk_fma_f32 v[128:129], v[128:129], v[144:145], v[210:211]
	v_pk_fma_f32 v[126:127], v[126:127], v[142:143], v[236:237]
	v_pk_fma_f32 v[210:211], v[124:125], v[140:141], v[212:213]
	v_pk_fma_f32 v[124:125], v[122:123], v[138:139], v[238:239]
	v_cvt_pk_bf16_f32 v122, v126, v127
	v_cvt_pk_bf16_f32 v123, v128, v129
	v_lshlrev_b32_e32 v126, 16, v216
	v_cvt_pk_bf16_f32 v124, v124, v125
	v_cvt_pk_bf16_f32 v125, v210, v211
	global_store_dwordx4 v[234:235], v[122:125], off
	v_and_b32_e32 v127, 0xffff0000, v216
	v_lshlrev_b32_e32 v128, 16, v217
	v_lshlrev_b32_e32 v122, 16, v214
	v_and_b32_e32 v123, 0xffff0000, v214
	v_and_b32_e32 v129, 0xffff0000, v217
	v_lshlrev_b32_e32 v124, 16, v215
	v_and_b32_e32 v125, 0xffff0000, v215
	v_pk_fma_f32 v[118:119], v[118:119], v[134:135], v[122:123]
	v_pk_fma_f32 v[122:123], v[116:117], v[132:133], v[128:129]
	v_pk_fma_f32 v[116:117], v[114:115], v[130:131], v[126:127]
	v_cvt_pk_bf16_f32 v114, v118, v119
	v_readlane_b32 s8, v255, 38
	v_pk_fma_f32 v[120:121], v[120:121], v[136:137], v[124:125]
	v_lshlrev_b32_e32 v118, 16, v219
	v_cvt_pk_bf16_f32 v115, v120, v121
	v_cvt_pk_bf16_f32 v116, v116, v117
	v_cvt_pk_bf16_f32 v117, v122, v123
	global_store_dwordx4 v[234:235], v[114:117], off offset:256
	v_and_b32_e32 v119, 0xffff0000, v219
	v_lshlrev_b32_e32 v120, 16, v220
	v_add_u32_e32 v114, s8, v209
	v_ashrrev_i32_e32 v115, 31, v114
	v_lshlrev_b64 v[114:115], 11, v[114:115]
	v_lshl_add_u64 v[114:115], s[94:95], 0, v[114:115]
	v_lshlrev_b32_e32 v116, 16, v218
	v_and_b32_e32 v117, 0xffff0000, v218
	v_and_b32_e32 v121, 0xffff0000, v220
	v_lshlrev_b32_e32 v122, 16, v221
	v_and_b32_e32 v123, 0xffff0000, v221
	v_lshl_add_u64 v[114:115], v[114:115], 0, v[168:169]
	v_pk_fma_f32 v[112:113], v[112:113], v[144:145], v[118:119]
	v_pk_fma_f32 v[110:111], v[110:111], v[142:143], v[116:117]
	v_pk_fma_f32 v[116:117], v[108:109], v[140:141], v[122:123]
	v_pk_fma_f32 v[108:109], v[106:107], v[138:139], v[120:121]
	v_cvt_pk_bf16_f32 v106, v110, v111
	v_cvt_pk_bf16_f32 v107, v112, v113
	v_lshlrev_b32_e32 v110, 16, v224
	v_cvt_pk_bf16_f32 v108, v108, v109
	v_cvt_pk_bf16_f32 v109, v116, v117
	global_store_dwordx4 v[114:115], v[106:109], off
	v_and_b32_e32 v111, 0xffff0000, v224
	v_lshlrev_b32_e32 v112, 16, v225
	v_lshlrev_b32_e32 v106, 16, v222
	v_and_b32_e32 v107, 0xffff0000, v222
	v_and_b32_e32 v113, 0xffff0000, v225
	v_lshlrev_b32_e32 v108, 16, v223
	v_and_b32_e32 v109, 0xffff0000, v223
	v_pk_fma_f32 v[102:103], v[102:103], v[134:135], v[106:107]
	v_pk_fma_f32 v[106:107], v[100:101], v[132:133], v[112:113]
	v_pk_fma_f32 v[100:101], v[98:99], v[130:131], v[110:111]
	v_cvt_pk_bf16_f32 v98, v102, v103
	v_readlane_b32 s8, v255, 39
	v_pk_fma_f32 v[104:105], v[104:105], v[136:137], v[108:109]
	v_lshlrev_b32_e32 v102, 16, v227
	v_cvt_pk_bf16_f32 v99, v104, v105
	v_cvt_pk_bf16_f32 v100, v100, v101
	v_cvt_pk_bf16_f32 v101, v106, v107
	global_store_dwordx4 v[114:115], v[98:101], off offset:256
	v_and_b32_e32 v103, 0xffff0000, v227
	v_lshlrev_b32_e32 v104, 16, v228
	v_add_u32_e32 v98, s8, v209
	v_ashrrev_i32_e32 v99, 31, v98
	v_lshlrev_b64 v[98:99], 11, v[98:99]
	v_lshl_add_u64 v[98:99], s[94:95], 0, v[98:99]
	v_lshlrev_b32_e32 v100, 16, v226
	v_and_b32_e32 v101, 0xffff0000, v226
	v_and_b32_e32 v105, 0xffff0000, v228
	v_lshlrev_b32_e32 v106, 16, v229
	v_and_b32_e32 v107, 0xffff0000, v229
	v_lshl_add_u64 v[98:99], v[98:99], 0, v[168:169]
	v_pk_fma_f32 v[94:95], v[94:95], v[144:145], v[102:103]
	v_pk_fma_f32 v[92:93], v[92:93], v[142:143], v[100:101]
	v_pk_fma_f32 v[100:101], v[90:91], v[140:141], v[106:107]
	v_pk_fma_f32 v[90:91], v[88:89], v[138:139], v[104:105]
	v_cvt_pk_bf16_f32 v88, v92, v93
	v_cvt_pk_bf16_f32 v89, v94, v95
	v_lshlrev_b32_e32 v92, 16, v232
	v_cvt_pk_bf16_f32 v90, v90, v91
	v_cvt_pk_bf16_f32 v91, v100, v101
	global_store_dwordx4 v[98:99], v[88:91], off
	v_and_b32_e32 v93, 0xffff0000, v232
	v_lshlrev_b32_e32 v94, 16, v233
	v_lshlrev_b32_e32 v88, 16, v230
	v_and_b32_e32 v89, 0xffff0000, v230
	v_and_b32_e32 v95, 0xffff0000, v233
	v_lshlrev_b32_e32 v90, 16, v231
; __device__ __forceinline__ unsigned cvt_pk_bf16(float lo, float hi) { unsigned r; asm volatile("v_cvt_pk_bf16_f32 %0, %1, %2" : "=v"(r) : "v"(lo), "v"(hi)); return r; }
; __device__ __forceinline__ float bf_lo(unsigned w) { return __uint_as_float(w << 16); }
; __device__ __forceinline__ float bf_hi(unsigned w) { return __uint_as_float(w & 0xffff0000u); }
;     __device__ __forceinline__ void operator()(const f32x4 (&acc)[2][2][4][2], const Unit& u, int wr, int wc, int fr, int fq) const {
;     ...
;             } else {
; #pragma unroll
;                 for (int ai = 0; ai < 2; ++ai) {
;                     u32x4 bb[4][2];
; #pragma unroll
;                     for (int m = 0; m < 4; ++m) { const bf16_t* bp = baseb + (size_t)(row_off + row0 + ai * HALF + m * 16) * DM + col0;
; #pragma unroll
;                         for (int bj = 0; bj < 2; ++bj) bb[m][bj] = *(const u32x4*)(bp + bj * HALF); }
;                     __builtin_amdgcn_sched_barrier(0);
; #pragma unroll
;                     for (int m = 0; m < 4; ++m) { bf16_t* op = outb + (size_t)(row_off + row0 + ai * HALF + m * 16) * DM + col0;
; #pragma unroll
;                         for (int bj = 0; bj < 2; ++bj) { const u32x4 ub = bb[m][bj];
;                             const f32x4 b0 = {bf_lo(ub.x), bf_hi(ub.x), bf_lo(ub.y), bf_hi(ub.y)}, b1 = {bf_lo(ub.z), bf_hi(ub.z), bf_lo(ub.w), bf_hi(ub.w)};
;                             const f32x4 v0 = b0 + gt[bj][0] * acc[ai][bj][m][0], v1 = b1 + gt[bj][1] * acc[ai][bj][m][1];
;                             u32x4 w; w.x = cvt_pk_bf16(v0[0], v0[1]); w.y = cvt_pk_bf16(v0[2], v0[3]); w.z = cvt_pk_bf16(v1[0], v1[1]); w.w = cvt_pk_bf16(v1[2], v1[3]);
;                             *(u32x4*)(op + bj * HALF) = w; } }
;                     __builtin_amdgcn_sched_barrier(0);
;                 }
;             }
	v_and_b32_e32 v91, 0xffff0000, v231
	v_pk_fma_f32 v[84:85], v[84:85], v[134:135], v[88:89]
	v_pk_fma_f32 v[88:89], v[82:83], v[132:133], v[94:95]
	v_pk_fma_f32 v[82:83], v[80:81], v[130:131], v[92:93]
	v_cvt_pk_bf16_f32 v80, v84, v85
	v_readlane_b32 s8, v255, 40
	v_pk_fma_f32 v[86:87], v[86:87], v[136:137], v[90:91]
	v_lshlrev_b32_e32 v84, 16, v151
	v_cvt_pk_bf16_f32 v81, v86, v87
	v_cvt_pk_bf16_f32 v82, v82, v83
	v_cvt_pk_bf16_f32 v83, v88, v89
	global_store_dwordx4 v[98:99], v[80:83], off offset:256
	v_and_b32_e32 v85, 0xffff0000, v151
	v_lshlrev_b32_e32 v86, 16, v152
	v_add_u32_e32 v80, s8, v209
	v_ashrrev_i32_e32 v81, 31, v80
	v_lshlrev_b64 v[80:81], 11, v[80:81]
	v_lshl_add_u64 v[80:81], s[94:95], 0, v[80:81]
	v_lshlrev_b32_e32 v82, 16, v150
	v_and_b32_e32 v83, 0xffff0000, v150
	v_and_b32_e32 v87, 0xffff0000, v152
	v_lshlrev_b32_e32 v88, 16, v153
	v_and_b32_e32 v89, 0xffff0000, v153
	v_lshl_add_u64 v[80:81], v[80:81], 0, v[168:169]
	v_pk_fma_f32 v[78:79], v[78:79], v[144:145], v[84:85]
	v_pk_fma_f32 v[76:77], v[76:77], v[142:143], v[82:83]
	v_pk_fma_f32 v[82:83], v[74:75], v[140:141], v[88:89]
	v_pk_fma_f32 v[74:75], v[72:73], v[138:139], v[86:87]
	v_cvt_pk_bf16_f32 v72, v76, v77
	v_cvt_pk_bf16_f32 v73, v78, v79
	v_lshlrev_b32_e32 v76, 16, v148
	v_cvt_pk_bf16_f32 v74, v74, v75
	v_cvt_pk_bf16_f32 v75, v82, v83
	global_store_dwordx4 v[80:81], v[72:75], off
	v_and_b32_e32 v77, 0xffff0000, v148
	v_lshlrev_b32_e32 v78, 16, v149
	v_lshlrev_b32_e32 v72, 16, v146
	v_and_b32_e32 v73, 0xffff0000, v146
	v_and_b32_e32 v79, 0xffff0000, v149
	v_lshlrev_b32_e32 v74, 16, v147
	v_and_b32_e32 v75, 0xffff0000, v147
	v_pk_fma_f32 v[68:69], v[68:69], v[134:135], v[72:73]
	v_pk_fma_f32 v[72:73], v[66:67], v[132:133], v[78:79]
	v_pk_fma_f32 v[66:67], v[64:65], v[130:131], v[76:77]
	v_pk_fma_f32 v[70:71], v[70:71], v[136:137], v[74:75]
	v_cvt_pk_bf16_f32 v64, v68, v69
	s_nop 0
	v_cvt_pk_bf16_f32 v65, v70, v71
	v_cvt_pk_bf16_f32 v66, v66, v67
	v_cvt_pk_bf16_f32 v67, v72, v73
	global_store_dwordx4 v[80:81], v[64:67], off offset:256
	v_lshlrev_b64 v[98:99], 11, v[176:177]
	s_nop 0
	v_lshl_add_u64 v[64:65], v[178:179], 0, v[98:99]
	global_load_dwordx4 v[72:75], v[64:65], off
	global_load_dwordx4 v[76:79], v[64:65], off offset:256
	v_or_b32_e32 v64, 16, v176
	v_ashrrev_i32_e32 v65, 31, v64
	v_lshlrev_b64 v[64:65], 11, v[64:65]
	v_lshl_add_u64 v[64:65], v[178:179], 0, v[64:65]
	global_load_dwordx4 v[80:83], v[64:65], off
	global_load_dwordx4 v[84:87], v[64:65], off offset:256
	v_or_b32_e32 v64, 32, v176
	v_ashrrev_i32_e32 v65, 31, v64
	v_lshlrev_b64 v[64:65], 11, v[64:65]
	v_lshl_add_u64 v[64:65], v[178:179], 0, v[64:65]
	global_load_dwordx4 v[88:91], v[64:65], off
	global_load_dwordx4 v[92:95], v[64:65], off offset:256
	v_or_b32_e32 v64, 48, v176
	v_ashrrev_i32_e32 v65, 31, v64
	v_lshlrev_b64 v[64:65], 11, v[64:65]
	v_lshl_add_u64 v[64:65], v[178:179], 0, v[64:65]
	global_load_dwordx4 v[68:71], v[64:65], off
	s_nop 0
	global_load_dwordx4 v[64:67], v[64:65], off offset:256
	s_waitcnt vmcnt(7)
	v_lshlrev_b32_e32 v100, 16, v72
	v_and_b32_e32 v101, 0xffff0000, v72
	v_lshlrev_b32_e32 v72, 16, v73
	v_and_b32_e32 v73, 0xffff0000, v73
	v_lshlrev_b32_e32 v102, 16, v74
	v_and_b32_e32 v103, 0xffff0000, v74
	v_lshlrev_b32_e32 v74, 16, v75
	v_and_b32_e32 v75, 0xffff0000, v75
	v_lshl_add_u64 v[98:99], s[94:95], 0, v[98:99]
	v_pk_fma_f32 v[62:63], v[62:63], v[144:145], v[72:73]
	v_pk_fma_f32 v[72:73], v[58:59], v[140:141], v[74:75]
	v_pk_fma_f32 v[58:59], v[56:57], v[138:139], v[102:103]
	v_lshl_add_u64 v[98:99], v[98:99], 0, v[168:169]
	v_pk_fma_f32 v[60:61], v[60:61], v[142:143], v[100:101]
	v_ashrrev_i32_e32 v175, 31, v174
	v_cvt_pk_bf16_f32 v56, v60, v61
	v_cvt_pk_bf16_f32 v57, v62, v63
	v_cvt_pk_bf16_f32 v58, v58, v59
	v_cvt_pk_bf16_f32 v59, v72, v73
	global_store_dwordx4 v[98:99], v[56:59], off
	s_waitcnt vmcnt(7)
	v_lshlrev_b32_e32 v60, 16, v78
	v_and_b32_e32 v61, 0xffff0000, v78
	v_lshlrev_b32_e32 v56, 16, v76
	v_and_b32_e32 v57, 0xffff0000, v76
	v_lshlrev_b32_e32 v58, 16, v77
	v_and_b32_e32 v59, 0xffff0000, v77
	v_lshlrev_b32_e32 v62, 16, v79
	v_and_b32_e32 v63, 0xffff0000, v79
	v_pk_fma_f32 v[54:55], v[54:55], v[136:137], v[58:59]
	v_pk_fma_f32 v[52:53], v[52:53], v[134:135], v[56:57]
	v_pk_fma_f32 v[56:57], v[50:51], v[132:133], v[62:63]
	v_pk_fma_f32 v[50:51], v[48:49], v[130:131], v[60:61]
	v_cvt_pk_bf16_f32 v48, v52, v53
	v_cvt_pk_bf16_f32 v49, v54, v55
	s_waitcnt vmcnt(6)
	v_lshlrev_b32_e32 v52, 16, v81
	v_cvt_pk_bf16_f32 v50, v50, v51
	v_cvt_pk_bf16_f32 v51, v56, v57
	global_store_dwordx4 v[98:99], v[48:51], off offset:256
	v_and_b32_e32 v53, 0xffff0000, v81
	v_lshlrev_b32_e32 v54, 16, v82
	v_lshlrev_b64 v[48:49], 11, v[174:175]
	v_lshl_add_u64 v[48:49], s[94:95], 0, v[48:49]
	v_lshlrev_b32_e32 v50, 16, v80
	v_and_b32_e32 v51, 0xffff0000, v80
	v_and_b32_e32 v55, 0xffff0000, v82
	v_lshlrev_b32_e32 v56, 16, v83
	v_and_b32_e32 v57, 0xffff0000, v83
	v_lshl_add_u64 v[48:49], v[48:49], 0, v[168:169]
	v_pk_fma_f32 v[46:47], v[46:47], v[144:145], v[52:53]
	v_pk_fma_f32 v[44:45], v[44:45], v[142:143], v[50:51]
	v_pk_fma_f32 v[50:51], v[42:43], v[140:141], v[56:57]
	v_pk_fma_f32 v[42:43], v[40:41], v[138:139], v[54:55]
	v_cvt_pk_bf16_f32 v40, v44, v45
	v_cvt_pk_bf16_f32 v41, v46, v47
	s_waitcnt vmcnt(6)
;     __device__ __forceinline__ void operator()(const f32x4 (&acc)[2][2][4][2], const Unit& u, int wr, int wc, int fr, int fq) const {
;     ...
;                     for (int m = 0; m < 4; ++m) { bf16_t* op = outb + (size_t)(row_off + row0 + ai * HALF + m * 16) * DM + col0;
; #pragma unroll
;                         for (int bj = 0; bj < 2; ++bj) { const u32x4 ub = bb[m][bj];
;                             const f32x4 b0 = {bf_lo(ub.x), bf_hi(ub.x), bf_lo(ub.y), bf_hi(ub.y)}, b1 = {bf_lo(ub.z), bf_hi(ub.z), bf_lo(ub.w), bf_hi(ub.w)};
;                             const f32x4 v0 = b0 + gt[bj][0] * acc[ai][bj][m][0], v1 = b1 + gt[bj][1] * acc[ai][bj][m][1];
;                             u32x4 w; w.x = cvt_pk_bf16(v0[0], v0[1]); w.y = cvt_pk_bf16(v0[2], v0[3]); w.z = cvt_pk_bf16(v1[0], v1[1]); w.w = cvt_pk_bf16(v1[2], v1[3]);
;                             *(u32x4*)(op + bj * HALF) = w; } }
;     ...
; #pragma unroll
;         for (int ai = 0; ai < 2; ++ai)
; #pragma unroll
;             for (int m = 0; m < 4; ++m) {
;                 const int row = row0 + ai * HALF + m * 16;
;                 bf16_t* rowp = O + (size_t)row * ldc + col0;
;                 f32x4 cs0 = {1.f, 0.f, 1.f, 0.f}, cs1 = {1.f, 0.f, 1.f, 0.f};
;                 if (mode == 1) {
;                     const int L1 = (1 << log2L) - 1, line = row >> log2L, uu = row & L1, rho = line & ((1 << log2d) - 1), pos = (uu << log2d) + rho;
;                     const float* tp = rope + ((size_t)pos * 32 + (wc & 1) * 16 + 4 * fq) * 2;
;                     cs0 = *(const f32x4*)tp; cs1 = *(const f32x4*)(tp + 4);
;                 }
; #pragma unroll
;                 for (int bj = 0; bj < 2; ++bj) {
;                     f32x4 v0 = acc[ai][bj][m][0], v1 = acc[ai][bj][m][1];
;                     if (mode == 2) {
; #pragma unroll
;                         for (int e = 0; e < 4; ++e) { float a = fmaxf(v0[e], 0.f), b = fmaxf(v1[e], 0.f); v0[e] = a * a; v1[e] = b * b; }
;                     } else if (mode == 1) {
;                         f32x4 r0, r1;
;                         r0[0] = v0[0] * cs0[0] - v0[1] * cs0[1]; r0[1] = v0[0] * cs0[1] + v0[1] * cs0[0];
;                         r0[2] = v0[2] * cs0[2] - v0[3] * cs0[3]; r0[3] = v0[2] * cs0[3] + v0[3] * cs0[2];
;                         r1[0] = v1[0] * cs1[0] - v1[1] * cs1[1]; r1[1] = v1[0] * cs1[1] + v1[1] * cs1[0];
	v_lshlrev_b32_e32 v44, 16, v86
	v_cvt_pk_bf16_f32 v42, v42, v43
	v_cvt_pk_bf16_f32 v43, v50, v51
	global_store_dwordx4 v[48:49], v[40:43], off
	v_and_b32_e32 v45, 0xffff0000, v86
	v_lshlrev_b32_e32 v46, 16, v87
	v_lshlrev_b32_e32 v40, 16, v84
	v_and_b32_e32 v41, 0xffff0000, v84
	v_and_b32_e32 v47, 0xffff0000, v87
	v_lshlrev_b32_e32 v42, 16, v85
	v_and_b32_e32 v43, 0xffff0000, v85
	v_pk_fma_f32 v[36:37], v[36:37], v[134:135], v[40:41]
	v_pk_fma_f32 v[40:41], v[34:35], v[132:133], v[46:47]
	v_pk_fma_f32 v[34:35], v[32:33], v[130:131], v[44:45]
	v_pk_fma_f32 v[38:39], v[38:39], v[136:137], v[42:43]
	v_cvt_pk_bf16_f32 v32, v36, v37
	v_ashrrev_i32_e32 v173, 31, v172
	v_cvt_pk_bf16_f32 v33, v38, v39
	v_cvt_pk_bf16_f32 v34, v34, v35
	v_cvt_pk_bf16_f32 v35, v40, v41
	global_store_dwordx4 v[48:49], v[32:35], off offset:256
	s_waitcnt vmcnt(7)
	v_lshlrev_b32_e32 v38, 16, v90
	v_and_b32_e32 v39, 0xffff0000, v90
	v_lshlrev_b64 v[32:33], 11, v[172:173]
	v_lshlrev_b32_e32 v34, 16, v88
	v_and_b32_e32 v35, 0xffff0000, v88
	v_lshlrev_b32_e32 v40, 16, v91
	v_and_b32_e32 v41, 0xffff0000, v91
	v_lshl_add_u64 v[32:33], s[94:95], 0, v[32:33]
	v_lshlrev_b32_e32 v36, 16, v89
	v_and_b32_e32 v37, 0xffff0000, v89
	v_pk_fma_f32 v[28:29], v[28:29], v[142:143], v[34:35]
	v_pk_fma_f32 v[34:35], v[26:27], v[140:141], v[40:41]
	v_pk_fma_f32 v[26:27], v[24:25], v[138:139], v[38:39]
	v_lshl_add_u64 v[32:33], v[32:33], 0, v[168:169]
	v_pk_fma_f32 v[30:31], v[30:31], v[144:145], v[36:37]
	v_cvt_pk_bf16_f32 v24, v28, v29
	s_waitcnt vmcnt(6)
	v_lshlrev_b32_e32 v28, 16, v94
	v_cvt_pk_bf16_f32 v25, v30, v31
	v_cvt_pk_bf16_f32 v26, v26, v27
	v_cvt_pk_bf16_f32 v27, v34, v35
	global_store_dwordx4 v[32:33], v[24:27], off
	v_and_b32_e32 v29, 0xffff0000, v94
	v_lshlrev_b32_e32 v30, 16, v95
	v_lshlrev_b32_e32 v24, 16, v92
	v_and_b32_e32 v25, 0xffff0000, v92
	v_lshlrev_b32_e32 v26, 16, v93
	v_and_b32_e32 v27, 0xffff0000, v93
	v_and_b32_e32 v31, 0xffff0000, v95
	v_pk_fma_f32 v[22:23], v[22:23], v[136:137], v[26:27]
	v_pk_fma_f32 v[20:21], v[20:21], v[134:135], v[24:25]
	v_pk_fma_f32 v[24:25], v[18:19], v[132:133], v[30:31]
	v_pk_fma_f32 v[18:19], v[16:17], v[130:131], v[28:29]
	v_cvt_pk_bf16_f32 v16, v20, v21
	v_cvt_pk_bf16_f32 v17, v22, v23
	v_ashrrev_i32_e32 v171, 31, v170
	v_cvt_pk_bf16_f32 v18, v18, v19
	v_cvt_pk_bf16_f32 v19, v24, v25
	global_store_dwordx4 v[32:33], v[16:19], off offset:256
	s_waitcnt vmcnt(7)
	v_lshlrev_b32_e32 v20, 16, v69
	v_and_b32_e32 v21, 0xffff0000, v69
	v_lshlrev_b64 v[16:17], 11, v[170:171]
	v_lshl_add_u64 v[16:17], s[94:95], 0, v[16:17]
	v_lshlrev_b32_e32 v18, 16, v68
	v_and_b32_e32 v19, 0xffff0000, v68
	v_lshlrev_b32_e32 v22, 16, v70
	v_and_b32_e32 v23, 0xffff0000, v70
	v_lshlrev_b32_e32 v24, 16, v71
	v_and_b32_e32 v25, 0xffff0000, v71
	v_lshl_add_u64 v[16:17], v[16:17], 0, v[168:169]
	v_pk_fma_f32 v[14:15], v[14:15], v[144:145], v[20:21]
	v_pk_fma_f32 v[12:13], v[12:13], v[142:143], v[18:19]
	v_pk_fma_f32 v[18:19], v[10:11], v[140:141], v[24:25]
	v_pk_fma_f32 v[10:11], v[8:9], v[138:139], v[22:23]
	v_cvt_pk_bf16_f32 v8, v12, v13
	v_cvt_pk_bf16_f32 v9, v14, v15
	s_waitcnt vmcnt(6)
	v_lshlrev_b32_e32 v12, 16, v66
	v_cvt_pk_bf16_f32 v10, v10, v11
	v_cvt_pk_bf16_f32 v11, v18, v19
	global_store_dwordx4 v[16:17], v[8:11], off
	v_and_b32_e32 v13, 0xffff0000, v66
	v_lshlrev_b32_e32 v14, 16, v67
	v_lshlrev_b32_e32 v8, 16, v64
	v_and_b32_e32 v9, 0xffff0000, v64
	v_and_b32_e32 v15, 0xffff0000, v67
	v_lshlrev_b32_e32 v10, 16, v65
	v_and_b32_e32 v11, 0xffff0000, v65
	v_pk_fma_f32 v[4:5], v[4:5], v[134:135], v[8:9]
	v_pk_fma_f32 v[8:9], v[2:3], v[132:133], v[14:15]
	v_pk_fma_f32 v[2:3], v[0:1], v[130:131], v[12:13]
	v_pk_fma_f32 v[6:7], v[6:7], v[136:137], v[10:11]
	v_cvt_pk_bf16_f32 v0, v4, v5
	s_nop 0
	v_cvt_pk_bf16_f32 v1, v6, v7
	v_cvt_pk_bf16_f32 v2, v2, v3
	v_cvt_pk_bf16_f32 v3, v8, v9
	global_store_dwordx4 v[16:17], v[0:3], off offset:256
	s_branch .LBB0_256
.Lmy_epi_relu:
	v_mul_lo_u32 v130, v209, s38
	s_lshl_b32 s8, s38, 5
	s_mul_i32 s9, s38, 0xa0
	v_add_lshl_u32 v130, v130, v146, 1
	v_max_f32_e32 v122, 0, v122
	v_max_f32_e32 v123, 0, v123
	v_max_f32_e32 v124, 0, v124
	v_max_f32_e32 v125, 0, v125
	v_max_f32_e32 v126, 0, v126
	v_max_f32_e32 v127, 0, v127
	v_max_f32_e32 v128, 0, v128
	v_max_f32_e32 v129, 0, v129
	v_mul_f32_e32 v122, v122, v122
	v_mul_f32_e32 v123, v123, v123
	v_mul_f32_e32 v124, v124, v124
	v_mul_f32_e32 v125, v125, v125
	v_mul_f32_e32 v126, v126, v126
	v_mul_f32_e32 v127, v127, v127
	v_mul_f32_e32 v128, v128, v128
	v_mul_f32_e32 v129, v129, v129
	v_cvt_pk_bf16_f32 v132, v126, v127
	v_cvt_pk_bf16_f32 v133, v128, v129
	v_cvt_pk_bf16_f32 v134, v122, v123
	v_cvt_pk_bf16_f32 v135, v124, v125
	global_store_dwordx4 v130, v[132:135], s[26:27]
	v_max_f32_e32 v114, 0, v114
	v_max_f32_e32 v115, 0, v115
	v_max_f32_e32 v116, 0, v116
	v_max_f32_e32 v117, 0, v117
	v_max_f32_e32 v118, 0, v118
	v_max_f32_e32 v119, 0, v119
	v_max_f32_e32 v120, 0, v120
	v_max_f32_e32 v121, 0, v121
	v_mul_f32_e32 v114, v114, v114
	v_mul_f32_e32 v115, v115, v115
	v_mul_f32_e32 v116, v116, v116
	v_mul_f32_e32 v117, v117, v117
	v_mul_f32_e32 v118, v118, v118
	v_mul_f32_e32 v119, v119, v119
	v_mul_f32_e32 v120, v120, v120
	v_mul_f32_e32 v121, v121, v121
	v_cvt_pk_bf16_f32 v136, v118, v119
	v_cvt_pk_bf16_f32 v137, v120, v121
	v_cvt_pk_bf16_f32 v138, v114, v115
	v_cvt_pk_bf16_f32 v139, v116, v117
	global_store_dwordx4 v130, v[136:139], s[26:27] offset:256
	s_nop 1
	v_add_u32_e32 v130, s8, v130
	v_max_f32_e32 v106, 0, v106
	v_max_f32_e32 v107, 0, v107
	v_max_f32_e32 v108, 0, v108
	v_max_f32_e32 v109, 0, v109
	v_max_f32_e32 v110, 0, v110
	v_max_f32_e32 v111, 0, v111
	v_max_f32_e32 v112, 0, v112
; __device__ __forceinline__ unsigned cvt_pk_bf16(float lo, float hi) { unsigned r; asm volatile("v_cvt_pk_bf16_f32 %0, %1, %2" : "=v"(r) : "v"(lo), "v"(hi)); return r; }
;     __device__ __forceinline__ void operator()(const f32x4 (&acc)[2][2][4][2], const Unit& u, int wr, int wc, int fr, int fq) const {
;     ...
; #pragma unroll
;         for (int ai = 0; ai < 2; ++ai)
; #pragma unroll
;             for (int m = 0; m < 4; ++m) {
;                 const int row = row0 + ai * HALF + m * 16;
;                 bf16_t* rowp = O + (size_t)row * ldc + col0;
;                 f32x4 cs0 = {1.f, 0.f, 1.f, 0.f}, cs1 = {1.f, 0.f, 1.f, 0.f};
;                 if (mode == 1) {
;                     const int L1 = (1 << log2L) - 1, line = row >> log2L, uu = row & L1, rho = line & ((1 << log2d) - 1), pos = (uu << log2d) + rho;
;                     const float* tp = rope + ((size_t)pos * 32 + (wc & 1) * 16 + 4 * fq) * 2;
;                     cs0 = *(const f32x4*)tp; cs1 = *(const f32x4*)(tp + 4);
;                 }
; #pragma unroll
;                 for (int bj = 0; bj < 2; ++bj) {
;                     f32x4 v0 = acc[ai][bj][m][0], v1 = acc[ai][bj][m][1];
;                     if (mode == 2) {
; #pragma unroll
;                         for (int e = 0; e < 4; ++e) { float a = fmaxf(v0[e], 0.f), b = fmaxf(v1[e], 0.f); v0[e] = a * a; v1[e] = b * b; }
;                     } else if (mode == 1) {
;                         f32x4 r0, r1;
;                         r0[0] = v0[0] * cs0[0] - v0[1] * cs0[1]; r0[1] = v0[0] * cs0[1] + v0[1] * cs0[0];
;                         r0[2] = v0[2] * cs0[2] - v0[3] * cs0[3]; r0[3] = v0[2] * cs0[3] + v0[3] * cs0[2];
;                         r1[0] = v1[0] * cs1[0] - v1[1] * cs1[1]; r1[1] = v1[0] * cs1[1] + v1[1] * cs1[0];
;                         r1[2] = v1[2] * cs1[2] - v1[3] * cs1[3]; r1[3] = v1[2] * cs1[3] + v1[3] * cs1[2];
;                         v0 = r0; v1 = r1;
;                     }
;                     u32x4 w; w.x = cvt_pk_bf16(v0[0], v0[1]); w.y = cvt_pk_bf16(v0[2], v0[3]); w.z = cvt_pk_bf16(v1[0], v1[1]); w.w = cvt_pk_bf16(v1[2], v1[3]);
;                     *(u32x4*)(rowp + bj * HALF) = w;
	v_max_f32_e32 v113, 0, v113
	v_mul_f32_e32 v106, v106, v106
	v_mul_f32_e32 v107, v107, v107
	v_mul_f32_e32 v108, v108, v108
	v_mul_f32_e32 v109, v109, v109
	v_mul_f32_e32 v110, v110, v110
	v_mul_f32_e32 v111, v111, v111
	v_mul_f32_e32 v112, v112, v112
	v_mul_f32_e32 v113, v113, v113
	v_cvt_pk_bf16_f32 v132, v110, v111
	v_cvt_pk_bf16_f32 v133, v112, v113
	v_cvt_pk_bf16_f32 v134, v106, v107
	v_cvt_pk_bf16_f32 v135, v108, v109
	global_store_dwordx4 v130, v[132:135], s[26:27]
	v_max_f32_e32 v98, 0, v98
	v_max_f32_e32 v99, 0, v99
	v_max_f32_e32 v100, 0, v100
	v_max_f32_e32 v101, 0, v101
	v_max_f32_e32 v102, 0, v102
	v_max_f32_e32 v103, 0, v103
	v_max_f32_e32 v104, 0, v104
	v_max_f32_e32 v105, 0, v105
	v_mul_f32_e32 v98, v98, v98
	v_mul_f32_e32 v99, v99, v99
	v_mul_f32_e32 v100, v100, v100
	v_mul_f32_e32 v101, v101, v101
	v_mul_f32_e32 v102, v102, v102
	v_mul_f32_e32 v103, v103, v103
	v_mul_f32_e32 v104, v104, v104
	v_mul_f32_e32 v105, v105, v105
	v_cvt_pk_bf16_f32 v136, v102, v103
	v_cvt_pk_bf16_f32 v137, v104, v105
	v_cvt_pk_bf16_f32 v138, v98, v99
	v_cvt_pk_bf16_f32 v139, v100, v101
	global_store_dwordx4 v130, v[136:139], s[26:27] offset:256
	s_nop 1
	v_add_u32_e32 v130, s8, v130
	v_max_f32_e32 v88, 0, v88
	v_max_f32_e32 v89, 0, v89
	v_max_f32_e32 v90, 0, v90
	v_max_f32_e32 v91, 0, v91
	v_max_f32_e32 v92, 0, v92
	v_max_f32_e32 v93, 0, v93
	v_max_f32_e32 v94, 0, v94
	v_max_f32_e32 v95, 0, v95
	v_mul_f32_e32 v88, v88, v88
	v_mul_f32_e32 v89, v89, v89
	v_mul_f32_e32 v90, v90, v90
	v_mul_f32_e32 v91, v91, v91
	v_mul_f32_e32 v92, v92, v92
	v_mul_f32_e32 v93, v93, v93
	v_mul_f32_e32 v94, v94, v94
	v_mul_f32_e32 v95, v95, v95
	v_cvt_pk_bf16_f32 v132, v92, v93
	v_cvt_pk_bf16_f32 v133, v94, v95
	v_cvt_pk_bf16_f32 v134, v88, v89
	v_cvt_pk_bf16_f32 v135, v90, v91
	global_store_dwordx4 v130, v[132:135], s[26:27]
	v_max_f32_e32 v80, 0, v80
	v_max_f32_e32 v81, 0, v81
	v_max_f32_e32 v82, 0, v82
	v_max_f32_e32 v83, 0, v83
	v_max_f32_e32 v84, 0, v84
	v_max_f32_e32 v85, 0, v85
	v_max_f32_e32 v86, 0, v86
	v_max_f32_e32 v87, 0, v87
	v_mul_f32_e32 v80, v80, v80
	v_mul_f32_e32 v81, v81, v81
	v_mul_f32_e32 v82, v82, v82
	v_mul_f32_e32 v83, v83, v83
	v_mul_f32_e32 v84, v84, v84
	v_mul_f32_e32 v85, v85, v85
	v_mul_f32_e32 v86, v86, v86
	v_mul_f32_e32 v87, v87, v87
	v_cvt_pk_bf16_f32 v136, v84, v85
	v_cvt_pk_bf16_f32 v137, v86, v87
	v_cvt_pk_bf16_f32 v138, v80, v81
	v_cvt_pk_bf16_f32 v139, v82, v83
	global_store_dwordx4 v130, v[136:139], s[26:27] offset:256
	s_nop 1
	v_add_u32_e32 v130, s8, v130
	v_max_f32_e32 v72, 0, v72
	v_max_f32_e32 v73, 0, v73
	v_max_f32_e32 v74, 0, v74
	v_max_f32_e32 v75, 0, v75
	v_max_f32_e32 v76, 0, v76
	v_max_f32_e32 v77, 0, v77
	v_max_f32_e32 v78, 0, v78
	v_max_f32_e32 v79, 0, v79
	v_mul_f32_e32 v72, v72, v72
	v_mul_f32_e32 v73, v73, v73
	v_mul_f32_e32 v74, v74, v74
	v_mul_f32_e32 v75, v75, v75
	v_mul_f32_e32 v76, v76, v76
	v_mul_f32_e32 v77, v77, v77
	v_mul_f32_e32 v78, v78, v78
	v_mul_f32_e32 v79, v79, v79
	v_cvt_pk_bf16_f32 v132, v76, v77
	v_cvt_pk_bf16_f32 v133, v78, v79
	v_cvt_pk_bf16_f32 v134, v72, v73
	v_cvt_pk_bf16_f32 v135, v74, v75
	global_store_dwordx4 v130, v[132:135], s[26:27]
	v_max_f32_e32 v64, 0, v64
	v_max_f32_e32 v65, 0, v65
	v_max_f32_e32 v66, 0, v66
	v_max_f32_e32 v67, 0, v67
	v_max_f32_e32 v68, 0, v68
	v_max_f32_e32 v69, 0, v69
	v_max_f32_e32 v70, 0, v70
	v_max_f32_e32 v71, 0, v71
	v_mul_f32_e32 v64, v64, v64
	v_mul_f32_e32 v65, v65, v65
	v_mul_f32_e32 v66, v66, v66
	v_mul_f32_e32 v67, v67, v67
	v_mul_f32_e32 v68, v68, v68
	v_mul_f32_e32 v69, v69, v69
	v_mul_f32_e32 v70, v70, v70
	v_mul_f32_e32 v71, v71, v71
	v_cvt_pk_bf16_f32 v136, v68, v69
	v_cvt_pk_bf16_f32 v137, v70, v71
	v_cvt_pk_bf16_f32 v138, v64, v65
	v_cvt_pk_bf16_f32 v139, v66, v67
	global_store_dwordx4 v130, v[136:139], s[26:27] offset:256
	s_nop 1
	v_add_u32_e32 v130, s9, v130
	v_max_f32_e32 v56, 0, v56
	v_max_f32_e32 v57, 0, v57
	v_max_f32_e32 v58, 0, v58
	v_max_f32_e32 v59, 0, v59
	v_max_f32_e32 v60, 0, v60
	v_max_f32_e32 v61, 0, v61
	v_max_f32_e32 v62, 0, v62
	v_max_f32_e32 v63, 0, v63
	v_mul_f32_e32 v56, v56, v56
	v_mul_f32_e32 v57, v57, v57
	v_mul_f32_e32 v58, v58, v58
	v_mul_f32_e32 v59, v59, v59
	v_mul_f32_e32 v60, v60, v60
	v_mul_f32_e32 v61, v61, v61
	v_mul_f32_e32 v62, v62, v62
	v_mul_f32_e32 v63, v63, v63
	v_cvt_pk_bf16_f32 v132, v60, v61
	v_cvt_pk_bf16_f32 v133, v62, v63
	v_cvt_pk_bf16_f32 v134, v56, v57
	v_cvt_pk_bf16_f32 v135, v58, v59
	global_store_dwordx4 v130, v[132:135], s[26:27]
	v_max_f32_e32 v48, 0, v48
	v_max_f32_e32 v49, 0, v49
	v_max_f32_e32 v50, 0, v50
	v_max_f32_e32 v51, 0, v51
	v_max_f32_e32 v52, 0, v52
	v_max_f32_e32 v53, 0, v53
	v_max_f32_e32 v54, 0, v54
	v_max_f32_e32 v55, 0, v55
	v_mul_f32_e32 v48, v48, v48
	v_mul_f32_e32 v49, v49, v49
	v_mul_f32_e32 v50, v50, v50
	v_mul_f32_e32 v51, v51, v51
	v_mul_f32_e32 v52, v52, v52
	v_mul_f32_e32 v53, v53, v53
	v_mul_f32_e32 v54, v54, v54
	v_mul_f32_e32 v55, v55, v55
	v_cvt_pk_bf16_f32 v136, v52, v53
	v_cvt_pk_bf16_f32 v137, v54, v55
	v_cvt_pk_bf16_f32 v138, v48, v49
	v_cvt_pk_bf16_f32 v139, v50, v51
	global_store_dwordx4 v130, v[136:139], s[26:27] offset:256
	s_nop 1
	v_add_u32_e32 v130, s8, v130
	v_max_f32_e32 v40, 0, v40
	v_max_f32_e32 v41, 0, v41
	v_max_f32_e32 v42, 0, v42
	v_max_f32_e32 v43, 0, v43
	v_max_f32_e32 v44, 0, v44
	v_max_f32_e32 v45, 0, v45
	v_max_f32_e32 v46, 0, v46
	v_max_f32_e32 v47, 0, v47
	v_mul_f32_e32 v40, v40, v40
	v_mul_f32_e32 v41, v41, v41
	v_mul_f32_e32 v42, v42, v42
	v_mul_f32_e32 v43, v43, v43
	v_mul_f32_e32 v44, v44, v44
	v_mul_f32_e32 v45, v45, v45
	v_mul_f32_e32 v46, v46, v46
	v_mul_f32_e32 v47, v47, v47
	v_cvt_pk_bf16_f32 v132, v44, v45
; __device__ __forceinline__ unsigned cvt_pk_bf16(float lo, float hi) { unsigned r; asm volatile("v_cvt_pk_bf16_f32 %0, %1, %2" : "=v"(r) : "v"(lo), "v"(hi)); return r; }
;     __device__ __forceinline__ void operator()(const f32x4 (&acc)[2][2][4][2], const Unit& u, int wr, int wc, int fr, int fq) const {
;     ...
; #pragma unroll
;         for (int ai = 0; ai < 2; ++ai)
; #pragma unroll
;             for (int m = 0; m < 4; ++m) {
;                 const int row = row0 + ai * HALF + m * 16;
;                 bf16_t* rowp = O + (size_t)row * ldc + col0;
;                 f32x4 cs0 = {1.f, 0.f, 1.f, 0.f}, cs1 = {1.f, 0.f, 1.f, 0.f};
;                 if (mode == 1) {
;                     const int L1 = (1 << log2L) - 1, line = row >> log2L, uu = row & L1, rho = line & ((1 << log2d) - 1), pos = (uu << log2d) + rho;
;                     const float* tp = rope + ((size_t)pos * 32 + (wc & 1) * 16 + 4 * fq) * 2;
;                     cs0 = *(const f32x4*)tp; cs1 = *(const f32x4*)(tp + 4);
;                 }
; #pragma unroll
;                 for (int bj = 0; bj < 2; ++bj) {
;                     f32x4 v0 = acc[ai][bj][m][0], v1 = acc[ai][bj][m][1];
;                     if (mode == 2) {
; #pragma unroll
;                         for (int e = 0; e < 4; ++e) { float a = fmaxf(v0[e], 0.f), b = fmaxf(v1[e], 0.f); v0[e] = a * a; v1[e] = b * b; }
;                     } else if (mode == 1) {
;                         f32x4 r0, r1;
;                         r0[0] = v0[0] * cs0[0] - v0[1] * cs0[1]; r0[1] = v0[0] * cs0[1] + v0[1] * cs0[0];
;                         r0[2] = v0[2] * cs0[2] - v0[3] * cs0[3]; r0[3] = v0[2] * cs0[3] + v0[3] * cs0[2];
;                         r1[0] = v1[0] * cs1[0] - v1[1] * cs1[1]; r1[1] = v1[0] * cs1[1] + v1[1] * cs1[0];
;                         r1[2] = v1[2] * cs1[2] - v1[3] * cs1[3]; r1[3] = v1[2] * cs1[3] + v1[3] * cs1[2];
;                         v0 = r0; v1 = r1;
;                     }
;                     u32x4 w; w.x = cvt_pk_bf16(v0[0], v0[1]); w.y = cvt_pk_bf16(v0[2], v0[3]); w.z = cvt_pk_bf16(v1[0], v1[1]); w.w = cvt_pk_bf16(v1[2], v1[3]);
;                     *(u32x4*)(rowp + bj * HALF) = w;
	v_cvt_pk_bf16_f32 v133, v46, v47
	v_cvt_pk_bf16_f32 v134, v40, v41
	v_cvt_pk_bf16_f32 v135, v42, v43
	global_store_dwordx4 v130, v[132:135], s[26:27]
	v_max_f32_e32 v32, 0, v32
	v_max_f32_e32 v33, 0, v33
	v_max_f32_e32 v34, 0, v34
	v_max_f32_e32 v35, 0, v35
	v_max_f32_e32 v36, 0, v36
	v_max_f32_e32 v37, 0, v37
	v_max_f32_e32 v38, 0, v38
	v_max_f32_e32 v39, 0, v39
	v_mul_f32_e32 v32, v32, v32
	v_mul_f32_e32 v33, v33, v33
	v_mul_f32_e32 v34, v34, v34
	v_mul_f32_e32 v35, v35, v35
	v_mul_f32_e32 v36, v36, v36
	v_mul_f32_e32 v37, v37, v37
	v_mul_f32_e32 v38, v38, v38
	v_mul_f32_e32 v39, v39, v39
	v_cvt_pk_bf16_f32 v136, v36, v37
	v_cvt_pk_bf16_f32 v137, v38, v39
	v_cvt_pk_bf16_f32 v138, v32, v33
	v_cvt_pk_bf16_f32 v139, v34, v35
	global_store_dwordx4 v130, v[136:139], s[26:27] offset:256
	s_nop 1
	v_add_u32_e32 v130, s8, v130
	v_max_f32_e32 v24, 0, v24
	v_max_f32_e32 v25, 0, v25
	v_max_f32_e32 v26, 0, v26
	v_max_f32_e32 v27, 0, v27
	v_max_f32_e32 v28, 0, v28
	v_max_f32_e32 v29, 0, v29
	v_max_f32_e32 v30, 0, v30
	v_max_f32_e32 v31, 0, v31
	v_mul_f32_e32 v24, v24, v24
	v_mul_f32_e32 v25, v25, v25
	v_mul_f32_e32 v26, v26, v26
	v_mul_f32_e32 v27, v27, v27
	v_mul_f32_e32 v28, v28, v28
	v_mul_f32_e32 v29, v29, v29
	v_mul_f32_e32 v30, v30, v30
	v_mul_f32_e32 v31, v31, v31
	v_cvt_pk_bf16_f32 v132, v28, v29
	v_cvt_pk_bf16_f32 v133, v30, v31
	v_cvt_pk_bf16_f32 v134, v24, v25
	v_cvt_pk_bf16_f32 v135, v26, v27
	global_store_dwordx4 v130, v[132:135], s[26:27]
	v_max_f32_e32 v16, 0, v16
	v_max_f32_e32 v17, 0, v17
	v_max_f32_e32 v18, 0, v18
	v_max_f32_e32 v19, 0, v19
	v_max_f32_e32 v20, 0, v20
	v_max_f32_e32 v21, 0, v21
	v_max_f32_e32 v22, 0, v22
	v_max_f32_e32 v23, 0, v23
	v_mul_f32_e32 v16, v16, v16
	v_mul_f32_e32 v17, v17, v17
	v_mul_f32_e32 v18, v18, v18
	v_mul_f32_e32 v19, v19, v19
	v_mul_f32_e32 v20, v20, v20
	v_mul_f32_e32 v21, v21, v21
	v_mul_f32_e32 v22, v22, v22
	v_mul_f32_e32 v23, v23, v23
	v_cvt_pk_bf16_f32 v136, v20, v21
	v_cvt_pk_bf16_f32 v137, v22, v23
	v_cvt_pk_bf16_f32 v138, v16, v17
	v_cvt_pk_bf16_f32 v139, v18, v19
	global_store_dwordx4 v130, v[136:139], s[26:27] offset:256
	s_nop 1
	v_add_u32_e32 v130, s8, v130
	v_max_f32_e32 v8, 0, v8
	v_max_f32_e32 v9, 0, v9
	v_max_f32_e32 v10, 0, v10
	v_max_f32_e32 v11, 0, v11
	v_max_f32_e32 v12, 0, v12
	v_max_f32_e32 v13, 0, v13
	v_max_f32_e32 v14, 0, v14
	v_max_f32_e32 v15, 0, v15
	v_mul_f32_e32 v8, v8, v8
	v_mul_f32_e32 v9, v9, v9
	v_mul_f32_e32 v10, v10, v10
	v_mul_f32_e32 v11, v11, v11
	v_mul_f32_e32 v12, v12, v12
	v_mul_f32_e32 v13, v13, v13
	v_mul_f32_e32 v14, v14, v14
	v_mul_f32_e32 v15, v15, v15
	v_cvt_pk_bf16_f32 v132, v12, v13
	v_cvt_pk_bf16_f32 v133, v14, v15
	v_cvt_pk_bf16_f32 v134, v8, v9
	v_cvt_pk_bf16_f32 v135, v10, v11
	global_store_dwordx4 v130, v[132:135], s[26:27]
	v_max_f32_e32 v0, 0, v0
	v_max_f32_e32 v1, 0, v1
	v_max_f32_e32 v2, 0, v2
	v_max_f32_e32 v3, 0, v3
	v_max_f32_e32 v4, 0, v4
	v_max_f32_e32 v5, 0, v5
	v_max_f32_e32 v6, 0, v6
	v_max_f32_e32 v7, 0, v7
	v_mul_f32_e32 v0, v0, v0
	v_mul_f32_e32 v1, v1, v1
	v_mul_f32_e32 v2, v2, v2
	v_mul_f32_e32 v3, v3, v3
	v_mul_f32_e32 v4, v4, v4
	v_mul_f32_e32 v5, v5, v5
	v_mul_f32_e32 v6, v6, v6
	v_mul_f32_e32 v7, v7, v7
	v_cvt_pk_bf16_f32 v136, v4, v5
	v_cvt_pk_bf16_f32 v137, v6, v7
	v_cvt_pk_bf16_f32 v138, v0, v1
	v_cvt_pk_bf16_f32 v139, v2, v3
	global_store_dwordx4 v130, v[136:139], s[26:27] offset:256
	s_branch .LBB0_256
.Lmy_epi_plain:
	v_mul_lo_u32 v130, v209, s38
	s_lshl_b32 s8, s38, 5
	s_mul_i32 s9, s38, 0xa0
	v_add_lshl_u32 v130, v130, v146, 1
	v_cvt_pk_bf16_f32 v132, v126, v127
	v_cvt_pk_bf16_f32 v133, v128, v129
	v_cvt_pk_bf16_f32 v134, v122, v123
	v_cvt_pk_bf16_f32 v135, v124, v125
	global_store_dwordx4 v130, v[132:135], s[26:27]
	v_cvt_pk_bf16_f32 v136, v118, v119
	v_cvt_pk_bf16_f32 v137, v120, v121
	v_cvt_pk_bf16_f32 v138, v114, v115
	v_cvt_pk_bf16_f32 v139, v116, v117
	global_store_dwordx4 v130, v[136:139], s[26:27] offset:256
	s_nop 1
	v_add_u32_e32 v130, s8, v130
	v_cvt_pk_bf16_f32 v132, v110, v111
	v_cvt_pk_bf16_f32 v133, v112, v113
	v_cvt_pk_bf16_f32 v134, v106, v107
	v_cvt_pk_bf16_f32 v135, v108, v109
	global_store_dwordx4 v130, v[132:135], s[26:27]
	v_cvt_pk_bf16_f32 v136, v102, v103
	v_cvt_pk_bf16_f32 v137, v104, v105
	v_cvt_pk_bf16_f32 v138, v98, v99
	v_cvt_pk_bf16_f32 v139, v100, v101
	global_store_dwordx4 v130, v[136:139], s[26:27] offset:256
	s_nop 1
	v_add_u32_e32 v130, s8, v130
	v_cvt_pk_bf16_f32 v132, v92, v93
	v_cvt_pk_bf16_f32 v133, v94, v95
	v_cvt_pk_bf16_f32 v134, v88, v89
	v_cvt_pk_bf16_f32 v135, v90, v91
	global_store_dwordx4 v130, v[132:135], s[26:27]
	v_cvt_pk_bf16_f32 v136, v84, v85
	v_cvt_pk_bf16_f32 v137, v86, v87
	v_cvt_pk_bf16_f32 v138, v80, v81
	v_cvt_pk_bf16_f32 v139, v82, v83
	global_store_dwordx4 v130, v[136:139], s[26:27] offset:256
	s_nop 1
	v_add_u32_e32 v130, s8, v130
	v_cvt_pk_bf16_f32 v132, v76, v77
	v_cvt_pk_bf16_f32 v133, v78, v79
	v_cvt_pk_bf16_f32 v134, v72, v73
	v_cvt_pk_bf16_f32 v135, v74, v75
	global_store_dwordx4 v130, v[132:135], s[26:27]
	v_cvt_pk_bf16_f32 v136, v68, v69
	v_cvt_pk_bf16_f32 v137, v70, v71
	v_cvt_pk_bf16_f32 v138, v64, v65
	v_cvt_pk_bf16_f32 v139, v66, v67
	global_store_dwordx4 v130, v[136:139], s[26:27] offset:256
	s_nop 1
	v_add_u32_e32 v130, s9, v130
	v_cvt_pk_bf16_f32 v132, v60, v61
	v_cvt_pk_bf16_f32 v133, v62, v63
	v_cvt_pk_bf16_f32 v134, v56, v57
	v_cvt_pk_bf16_f32 v135, v58, v59
	global_store_dwordx4 v130, v[132:135], s[26:27]
	v_cvt_pk_bf16_f32 v136, v52, v53
	v_cvt_pk_bf16_f32 v137, v54, v55
	v_cvt_pk_bf16_f32 v138, v48, v49
	v_cvt_pk_bf16_f32 v139, v50, v51
	global_store_dwordx4 v130, v[136:139], s[26:27] offset:256
	s_nop 1
	v_add_u32_e32 v130, s8, v130
	v_cvt_pk_bf16_f32 v132, v44, v45
	v_cvt_pk_bf16_f32 v133, v46, v47
	v_cvt_pk_bf16_f32 v134, v40, v41
	v_cvt_pk_bf16_f32 v135, v42, v43
	global_store_dwordx4 v130, v[132:135], s[26:27]
	v_cvt_pk_bf16_f32 v136, v36, v37
	v_cvt_pk_bf16_f32 v137, v38, v39
	v_cvt_pk_bf16_f32 v138, v32, v33
	v_cvt_pk_bf16_f32 v139, v34, v35
	global_store_dwordx4 v130, v[136:139], s[26:27] offset:256
	s_nop 1
	v_add_u32_e32 v130, s8, v130
	v_cvt_pk_bf16_f32 v132, v28, v29
	v_cvt_pk_bf16_f32 v133, v30, v31
	v_cvt_pk_bf16_f32 v134, v24, v25
	v_cvt_pk_bf16_f32 v135, v26, v27
	global_store_dwordx4 v130, v[132:135], s[26:27]
	v_cvt_pk_bf16_f32 v136, v20, v21
	v_cvt_pk_bf16_f32 v137, v22, v23
	v_cvt_pk_bf16_f32 v138, v16, v17
	v_cvt_pk_bf16_f32 v139, v18, v19
	global_store_dwordx4 v130, v[136:139], s[26:27] offset:256
	s_nop 1
	v_add_u32_e32 v130, s8, v130
	v_cvt_pk_bf16_f32 v132, v12, v13
	v_cvt_pk_bf16_f32 v133, v14, v15
	v_cvt_pk_bf16_f32 v134, v8, v9
	v_cvt_pk_bf16_f32 v135, v10, v11
	global_store_dwordx4 v130, v[132:135], s[26:27]
	v_cvt_pk_bf16_f32 v136, v4, v5
	v_cvt_pk_bf16_f32 v137, v6, v7
	v_cvt_pk_bf16_f32 v138, v0, v1
	v_cvt_pk_bf16_f32 v139, v2, v3
	global_store_dwordx4 v130, v[136:139], s[26:27] offset:256
	s_branch .LBB0_256

; __device__ __forceinline__ int tid_() { int t = (int)threadIdx.x; asm volatile("" : "+v"(t)); return t; }
; __device__ __forceinline__ int v_st(int k, int c) { const int kk = (k & ~0xC) | ((k & 4) << 1) | ((k & 8) >> 1); return ((kk >> 3) * 4 + (c >> 5)) * 512 + ((kk & 7) * 32 + (c & 31)) * 2; }
; __device__ __forceinline__ int v_rd_base(int lane) { return ((lane & 3) << 3) | (((lane >> 2) & 3) << 6) | (((lane >> 4) & 1) << 5) | (((lane >> 5) & 1) << 8); }
; __device__ __forceinline__ void qkt(f32x16& p0, f32x16& p1, const bf16_t* Ks, const bf16x8* qr, int r32, int hi) {
;     p0 = f32x16{}; p1 = f32x16{};
; #pragma unroll
;     for (int d0 = 0; d0 < 8; ++d0) { int cb = (d0 * 16 + hi * 8) * 2;
;         bf16x8 b0 = *reinterpret_cast<const bf16x8*>((const char*)Ks + KSWZ(r32, cb));
;         bf16x8 b1 = *reinterpret_cast<const bf16x8*>((const char*)Ks + KSWZ(32 + r32, cb));
;         p0 = __builtin_amdgcn_mfma_f32_32x32x16_bf16(b0, qr[d0], p0, 0, 0, 0);
;         p1 = __builtin_amdgcn_mfma_f32_32x32x16_bf16(b1, qr[d0], p1, 0, 0, 0); }
; __device__ __forceinline__ void attn_dense_body(const bf16_t* __restrict__ Qb, const bf16_t* __restrict__ Kh, const bf16_t* __restrict__ Vh,
;                                                 bf16_t* __restrict__ Ob, int seq, char* lds, int dry) {
;     const int tid = tid_(), wid = tid >> 6, lane = tid & 63, r32 = lane & 31, hi = lane >> 5;
;     bf16_t* V_lds = (bf16_t*)lds; bf16_t* K_lds = (bf16_t*)(lds + 3 * SHM_V);
;     float* ws = (float*)(lds + 3 * SHM_V + 3 * SHM_K) + wid * 64; float* li_l = ws; float* al_l = ws + 32;
;     float m_reg = -1e30f, l_reg = 0; f32x16 o[4] = {}; bf16x8 qr[8];
;     const bf16_t* Qw = Qb + (long)(wid * QBLK + r32) * LDQ + hi * 8;
; #pragma unroll
;     for (int d0 = 0; d0 < 8; ++d0) qr[d0] = *reinterpret_cast<const bf16x8*>(Qw + d0 * 16);
;     const int sr = tid >> 4, sc = (tid & 15) * 8, vst0 = v_st(sr, sc), vst1 = v_st(32 + sr, sc);
;     const int vb0 = (int)(uintptr_t)V_lds + v_rd_base(lane);
;     bf16x8 sv0[2], sv1[2], sk0[2], sk1[2];
;     ...
;     f32x16 pA0, pA1, pB0, pB1; float mnA, mnB, alA, alB; bf16x8 pa0, pa1, pa2, pa3; const int NT = seq / KVBLK;
;     SLOAD(0, 0); asm volatile("s_waitcnt vmcnt(0)" ::: "memory"); SWRITE(0, 0); __syncthreads();
;     qkt(pA0, pA1, K_lds, qr, r32, hi); partialSM(pA0, pA1, m_reg, mnA, alA);
.LBB0_268:
	s_lshl_b32 s4, s29, 5
	s_cmpk_lt_i32 s29, 0x400
	s_movk_i32 s7, 0xc000
	s_cselect_b32 s5, 6, 4
	s_cselect_b32 s6, 63, 15
	s_cselect_b32 s7, s7, 0x7ffff000
	s_movk_i32 s37, 0x4000
	s_cselect_b32 s8, s37, 0xffff8000
	s_cselect_b32 s36, 0x100, 64
	s_lshr_b32 s12, s29, s5
	s_and_b32 s5, s6, s29
	s_and_b32 s4, s7, s4
	s_add_i32 s8, s4, s8
	s_lshl_b32 s4, s5, 8
	s_add_i32 s4, s8, s4
	s_and_b32 s6, s12, 7
	s_ashr_i32 s5, s4, 31
	s_mul_i32 s9, s4, 0xc00
	s_mul_hi_i32 s7, s4, 0xc00
	s_add_u32 s9, s30, s9
	s_addc_u32 s7, s31, s7
	s_lshl_b32 s35, s6, 7
	s_lshl_b32 s6, s6, 8
	s_add_u32 s10, s9, s6
	s_addc_u32 s11, s7, 0
	s_ashr_i32 s9, s8, 31
	s_mul_i32 s7, s8, 0xc00
	s_mul_hi_i32 s6, s8, 0xc00
	s_add_u32 s7, s30, s7
	s_addc_u32 s13, s31, s6
	s_lshl_b32 s6, s12, 6
	s_and_b32 s39, s6, 0x100
	v_mov_b32_e32 v70, v182
	s_add_u32 s6, s7, s39
	s_addc_u32 s7, s13, 0
	v_ashrrev_i32_e32 v48, 4, v70
	v_lshlrev_b32_e32 v18, 3, v70
	v_and_b32_e32 v71, 0x78, v18
	s_waitcnt vmcnt(0)
	v_mad_i64_i32 v[0:1], s[12:13], v48, s71, 0
	v_add_u32_e32 v19, 32, v48
	v_or_b32_e32 v0, v0, v71
	v_lshl_add_u64 v[8:9], v[0:1], 1, s[6:7]
	v_mad_i64_i32 v[4:5], s[12:13], v19, s71, 0
	global_load_dwordx4 v[0:3], v[8:9], off offset:2560
	v_or_b32_e32 v4, v4, v71
	v_lshl_add_u64 v[12:13], v[4:5], 1, s[6:7]
	global_load_dwordx4 v[4:7], v[12:13], off offset:2560
	s_nop 0
	global_load_dwordx4 v[8:11], v[8:9], off offset:2048
	s_nop 0
	global_load_dwordx4 v[12:15], v[12:13], off offset:2048
	v_ashrrev_i32_e32 v49, 1, v70
	s_movk_i32 s12, 0xffe0
	v_bfe_u32 v207, v70, 5, 1
	v_bfi_b32 v20, s12, v49, v70
	v_mov_b64_e32 v[16:17], s[10:11]
	v_mad_i64_i32 v[16:17], s[10:11], v20, s70, v[16:17]
	v_lshlrev_b32_e32 v96, 4, v207
	v_lshl_add_u64 v[16:17], v[16:17], 0, v[96:97]
	global_load_dwordx4 v[126:129], v[16:17], off
	global_load_dwordx4 v[122:125], v[16:17], off offset:32
	global_load_dwordx4 v[118:121], v[16:17], off offset:64
	global_load_dwordx4 v[114:117], v[16:17], off offset:96
	global_load_dwordx4 v[110:113], v[16:17], off offset:128
	global_load_dwordx4 v[106:109], v[16:17], off offset:160
	global_load_dwordx4 v[102:105], v[16:17], off offset:192
	global_load_dwordx4 v[98:101], v[16:17], off offset:224
	v_and_b32_e32 v21, 0xfffff0, v48
	v_lshlrev_b32_e32 v22, 1, v48
	v_lshrrev_b32_e32 v23, 1, v48
	v_and_b32_e32 v24, 3, v48
	v_and_or_b32 v21, v22, 8, v21
	v_and_or_b32 v22, v23, 4, v24
	v_and_b32_e32 v24, 0xfffff0, v19
	v_lshlrev_b32_e32 v26, 1, v19
	v_bfe_u32 v18, v18, 5, 2
	v_lshrrev_b32_e32 v21, 1, v21
	v_and_or_b32 v24, v26, 8, v24
	v_lshlrev_b32_e32 v23, 1, v71
	v_or_b32_e32 v21, v21, v18
	v_lshrrev_b32_e32 v24, 1, v24
	v_lshlrev_b32_e32 v22, 6, v22
	v_and_b32_e32 v27, 48, v23
	v_lshlrev_b32_e32 v21, 9, v21
	v_or_b32_e32 v18, v24, v18
	v_and_b32_e32 v20, 0x70, v70
	v_lshlrev_b32_e32 v25, 8, v48
	v_or3_b32 v216, v21, v22, v27
	v_lshlrev_b32_e32 v18, 9, v18
	v_bitop3_b32 v214, v23, v25, v20 bitop3:0xde
	v_and_b32_e32 v252, 0x80, v182
	v_lshlrev_b32_e32 v253, 4, v182
	v_and_b32_e32 v253, 0x80, v253
	v_xor_b32_e32 v214, v214, v252
	v_or3_b32 v217, v18, v22, v27
	v_add_u32_e32 v72, 0, v216
	v_and_b32_e32 v208, 31, v70
	v_lshlrev_b32_e32 v50, 4, v70
	v_add_u32_e32 v73, 0, v217
	s_waitcnt vmcnt(0)
	s_add_i32 s10, 0, 0x18000
	v_and_b32_e32 v74, 63, v70
	s_cmp_lg_u32 0, -1
	s_mov_b32 s12, 0
	s_mov_b32 s13, s12
	v_and_b32_e32 v178, 0xffffffe0, v49
	s_waitcnt vmcnt(11)
	ds_write_b128 v72, v[0:3]
	s_waitcnt vmcnt(10)
	ds_write_b128 v73, v[4:7]
	v_add_u32_e32 v0, 0, v214
	s_waitcnt vmcnt(9)
	ds_write_b128 v0, v[8:11] offset:49152
	v_lshlrev_b32_e32 v0, 8, v19
	v_lshlrev_b32_e32 v8, 8, v208
	v_and_b32_e32 v9, 0x70, v50
	v_bitop3_b32 v219, v23, v0, v20 bitop3:0xde
	v_xor_b32_e32 v219, v219, v252
	v_bitop3_b32 v220, v96, v8, v9 bitop3:0xde
	v_xor_b32_e32 v220, v220, v253
	v_add_u32_e32 v0, 0, v219
	v_add_u32_e32 v4, 0, v220
	s_waitcnt vmcnt(8)
	ds_write_b128 v0, v[12:15] offset:49152
	s_waitcnt lgkmcnt(0)
	s_barrier
	ds_read_b128 v[0:3], v4 offset:49152
	ds_read_b128 v[4:7], v4 offset:57344
	s_waitcnt vmcnt(7) lgkmcnt(1)
	v_mfma_f32_32x32x16_bf16 v[16:31], v[0:3], v[126:129], 0
	v_or_b32_e32 v0, 32, v96
	v_bitop3_b32 v222, v0, v8, v9 bitop3:0xde
	v_xor_b32_e32 v222, v222, v253
	v_ashrrev_i32_e32 v49, 31, v48
	s_mov_b32 s14, s12
	s_mov_b32 s15, s12
	s_mov_b32 s16, s12
	s_mov_b32 s17, s12
	s_waitcnt lgkmcnt(0)
	v_mfma_f32_32x32x16_bf16 v[32:47], v[4:7], v[126:129], 0
	v_add_u32_e32 v4, 0, v222
	ds_read_b128 v[0:3], v4 offset:49152
	ds_read_b128 v[4:7], v4 offset:57344
	s_mov_b32 s18, s12
	s_mov_b32 s19, s12
	s_mov_b32 s20, s12
	s_mov_b32 s21, s12
	s_mov_b32 s22, s12
	s_waitcnt vmcnt(6) lgkmcnt(1)
	v_mfma_f32_32x32x16_bf16 v[16:31], v[0:3], v[122:125], v[16:31]
	v_or_b32_e32 v0, 64, v96
	v_bitop3_b32 v221, v0, v8, v9 bitop3:0xde
	v_xor_b32_e32 v221, v221, v253
	s_mov_b32 s23, s12
	s_mov_b32 s24, s12
	s_mov_b32 s25, s12
	s_mov_b32 s26, s12
	s_mov_b32 s27, s12
	s_waitcnt lgkmcnt(0)
	v_mfma_f32_32x32x16_bf16 v[32:47], v[4:7], v[122:125], v[32:47]
	v_add_u32_e32 v4, 0, v221
	ds_read_b128 v[0:3], v4 offset:49152
	ds_read_b128 v[4:7], v4 offset:57344
	s_mov_b32 s38, 2
	v_mov_b32_e32 v210, 0
	s_waitcnt vmcnt(5) lgkmcnt(1)
	v_mfma_f32_32x32x16_bf16 v[16:31], v[0:3], v[118:121], v[16:31]
	v_or_b32_e32 v0, 0x60, v96
	v_bitop3_b32 v218, v0, v8, v9 bitop3:0xde
	v_xor_b32_e32 v218, v218, v253
	s_waitcnt lgkmcnt(0)
	v_mfma_f32_32x32x16_bf16 v[32:47], v[4:7], v[118:121], v[32:47]
	v_add_u32_e32 v4, 0, v218
	ds_read_b128 v[0:3], v4 offset:49152
	ds_read_b128 v[4:7], v4 offset:57344
	s_waitcnt vmcnt(4) lgkmcnt(1)
; #define SLOAD(i, k0) do { sv0[i] = *(const bf16x8*)(&Vh[(long)((k0) + sr) * LDK + sc]); sv1[i] = *(const bf16x8*)(&Vh[(long)((k0) + 32 + sr) * LDK + sc]); \
;     sk0[i] = *(const bf16x8*)(&Kh[(long)((k0) + sr) * LDK + sc]); sk1[i] = *(const bf16x8*)(&Kh[(long)((k0) + 32 + sr) * LDK + sc]); } while (0)
; #define SWRITE(off, i) do { *(bf16x8*)((char*)V_lds + (off) + vst0) = sv0[i];          \
;     *(bf16x8*)((char*)V_lds + (off) + vst1) = sv1[i]; int kc = sc * 2;               \
;     *(bf16x8*)((char*)K_lds + (off) + KSWZ(sr, kc)) = sk0[i];                       \
;     *(bf16x8*)((char*)K_lds + (off) + KSWZ(32 + sr, kc)) = sk1[i]; } while (0)
; #define SWAIT() asm volatile("s_waitcnt vmcnt(4)" ::: "memory")
; __device__ __forceinline__ void partialSM(f32x16& p0, f32x16& p1, float& m_reg, float& mn, float& alpha) {
;     constexpr float C = SCALE * 1.4426950408889634f;
;     float pmax = p0[0];
; #pragma unroll
;     for (int r = 1; r < 16; ++r) pmax = fmaxf(pmax, p0[r]);
; #pragma unroll
;     for (int r = 0; r < 16; ++r) pmax = fmaxf(pmax, p1[r]);
;     { auto rr = __builtin_amdgcn_permlane32_swap(__float_as_uint(pmax), __float_as_uint(pmax), false, false);
;       pmax = fmaxf(__uint_as_float(rr[0]), __uint_as_float(rr[1])); }
;     if (__builtin_expect(__all(pmax - m_reg <= THR / SCALE), 1)) { mn = m_reg; alpha = 1.f; }
;     else { mn = fmaxf(m_reg, pmax); alpha = __builtin_amdgcn_exp2f((m_reg - mn) * C); m_reg = mn; }
; __device__ __forceinline__ void attn_dense_body(const bf16_t* __restrict__ Qb, const bf16_t* __restrict__ Kh, const bf16_t* __restrict__ Vh,
;                                                 bf16_t* __restrict__ Ob, int seq, char* lds, int dry) {
;     ...
;     qkt(pA0, pA1, K_lds, qr, r32, hi); partialSM(pA0, pA1, m_reg, mnA, alA);
;     SLOAD(1, KVBLK); if (2 < NT) SLOAD(0, 2 * KVBLK);
;     SWAIT(); SWRITE((int)SHM_K, 1); __syncthreads();
	v_mfma_f32_32x32x16_bf16 v[16:31], v[0:3], v[114:117], v[16:31]
	v_or_b32_e32 v0, 0x80, v96
	v_bitop3_b32 v215, v0, v8, v9 bitop3:0xde
	v_xor_b32_e32 v215, v215, v253
	s_waitcnt lgkmcnt(0)
	v_mfma_f32_32x32x16_bf16 v[32:47], v[4:7], v[114:117], v[32:47]
	v_add_u32_e32 v4, 0, v215
	ds_read_b128 v[0:3], v4 offset:49152
	ds_read_b128 v[4:7], v4 offset:57344
	s_waitcnt vmcnt(3) lgkmcnt(1)
	v_mfma_f32_32x32x16_bf16 v[16:31], v[0:3], v[110:113], v[16:31]
	v_or_b32_e32 v0, 0xa0, v96
	v_bitop3_b32 v213, v0, v8, v9 bitop3:0xde
	v_xor_b32_e32 v213, v213, v253
	s_waitcnt lgkmcnt(0)
	v_mfma_f32_32x32x16_bf16 v[32:47], v[4:7], v[110:113], v[32:47]
	v_add_u32_e32 v4, 0, v213
	ds_read_b128 v[0:3], v4 offset:49152
	v_and_b32_e32 v5, 0x3fffffc0, v70
	v_lshl_add_u32 v179, v5, 2, s10
	ds_read_b128 v[4:7], v4 offset:57344
	v_lshl_add_u32 v209, v208, 2, v179
	s_waitcnt vmcnt(2) lgkmcnt(1)
	v_mfma_f32_32x32x16_bf16 v[16:31], v[0:3], v[106:109], v[16:31]
	v_lshlrev_b32_e32 v0, 3, v74
	v_and_b32_e32 v1, 0xc0, v50
	v_and_or_b32 v10, v0, 24, v1
	v_lshlrev_b32_e32 v1, 1, v70
	v_and_b32_e32 v12, 0x100, v0
	v_add_u32_e32 v0, 64, v48
	v_and_b32_e32 v11, 32, v1
	s_waitcnt lgkmcnt(0)
	v_mfma_f32_32x32x16_bf16 v[32:47], v[4:7], v[106:109], v[32:47]
	v_or_b32_e32 v6, 0xc0, v96
	v_mad_i64_i32 v[0:1], s[10:11], v0, s71, 0
	v_add_u32_e32 v2, 0x60, v48
	v_or_b32_e32 v0, v0, v71
	v_mad_i64_i32 v[2:3], s[10:11], v2, s71, 0
	v_bitop3_b32 v223, v6, v8, v9 bitop3:0xde
	v_xor_b32_e32 v223, v223, v253
	v_lshl_add_u64 v[0:1], v[0:1], 1, s[6:7]
	v_or_b32_e32 v2, v2, v71
	v_add_u32_e32 v6, 0, v223
	global_load_dwordx4 v[50:53], v[0:1], off offset:2560
	global_load_dwordx4 v[58:61], v[0:1], off offset:2048
	v_lshl_add_u64 v[4:5], v[2:3], 1, s[6:7]
	ds_read_b128 v[0:3], v6 offset:49152
	s_waitcnt vmcnt(3) lgkmcnt(0)
	v_mfma_f32_32x32x16_bf16 v[16:31], v[0:3], v[102:105], v[16:31]
	v_or_b32_e32 v0, 0xe0, v96
	v_bitop3_b32 v224, v0, v8, v9 bitop3:0xde
	v_xor_b32_e32 v224, v224, v253
	global_load_dwordx4 v[54:57], v[4:5], off offset:2560
	global_load_dwordx4 v[62:65], v[4:5], off offset:2048
	v_or3_b32 v4, v10, v11, v12
	s_cselect_b32 s10, 0, 0
	v_add_u32_e32 v8, 0, v224
	v_add_u32_e32 v212, s10, v4
	ds_read_b128 v[4:7], v6 offset:57344
	ds_read_b128 v[0:3], v8 offset:49152
	ds_read_b128 v[66:69], v8 offset:57344
	s_waitcnt lgkmcnt(2)
	v_mfma_f32_32x32x16_bf16 v[32:47], v[4:7], v[102:105], v[32:47]
	s_waitcnt vmcnt(4) lgkmcnt(1)
	v_mfma_f32_32x32x16_bf16 v[16:31], v[0:3], v[98:101], v[16:31]
	v_mov_b64_e32 v[0:1], s[12:13]
	v_mov_b64_e32 v[2:3], s[14:15]
	v_mov_b64_e32 v[4:5], s[16:17]
	v_mov_b64_e32 v[6:7], s[18:19]
	v_mov_b64_e32 v[8:9], s[20:21]
	v_mov_b64_e32 v[10:11], s[22:23]
	v_mov_b64_e32 v[12:13], s[24:25]
	s_waitcnt lgkmcnt(0)
	v_mfma_f32_32x32x16_bf16 v[32:47], v[66:69], v[98:101], v[32:47]
	s_nop 2
	v_max_f32_e32 v66, v17, v17
	v_max_f32_e32 v67, v16, v16
	v_max_f32_e32 v66, v67, v66
	v_max3_f32 v66, v66, v18, v19
	v_max3_f32 v66, v66, v20, v21
	v_max3_f32 v66, v66, v22, v23
	v_max3_f32 v66, v66, v24, v25
	v_max3_f32 v66, v66, v26, v27
	v_max3_f32 v66, v66, v28, v29
	v_max3_f32 v66, v66, v30, v31
	v_max3_f32 v66, v66, v32, v33
	v_max3_f32 v66, v66, v34, v35
	v_max3_f32 v66, v66, v36, v37
	v_max3_f32 v66, v66, v38, v39
	v_max3_f32 v66, v66, v40, v41
	v_max3_f32 v66, v66, v42, v43
	v_max3_f32 v66, v66, v44, v45
	v_max3_f32 v75, v66, v46, v47
	v_mov_b32_e32 v66, v75
	s_nop 1
	v_permlane32_swap_b32_e32 v75, v66
	v_max_f32_e32 v76, v66, v66
	v_add_u32_e32 v66, 0xa0, v48
	v_mad_i64_i32 v[66:67], s[10:11], v66, s71, 0
	v_add_u32_e32 v68, 0x80, v48
	v_or_b32_e32 v66, v66, v71
	v_mad_i64_i32 v[68:69], s[10:11], v68, s71, 0
	v_lshl_add_u64 v[66:67], v[66:67], 1, s[6:7]
	v_or_b32_e32 v68, v68, v71
	v_lshl_add_u64 v[68:69], v[68:69], 1, s[6:7]
	global_load_dwordx4 v[130:133], v[66:67], off offset:2048
	global_load_dwordx4 v[142:145], v[66:67], off offset:2560
	global_load_dwordx4 v[138:141], v[68:69], off offset:2048
	global_load_dwordx4 v[134:137], v[68:69], off offset:2560
	v_max_f32_e32 v66, v75, v75
	v_max_f32_e32 v66, v66, v76
	v_add_f32_e32 v67, 0x7149f2ca, v66
	s_add_i32 s6, 0, 0x10000
	v_cmp_ge_f32_e32 vcc, s72, v67
	s_waitcnt vmcnt(4)
	s_waitcnt vmcnt(7)
	ds_write_b128 v72, v[50:53] offset:16384
	s_waitcnt vmcnt(5)
	ds_write_b128 v73, v[54:57] offset:16384
	v_add_u32_e32 v50, s6, v214
	ds_write_b128 v50, v[58:61]
	v_add_u32_e32 v50, s6, v219
	s_cmp_eq_u64 vcc, exec
	s_waitcnt vmcnt(4)
; __device__ __forceinline__ void partialSM(f32x16& p0, f32x16& p1, float& m_reg, float& mn, float& alpha) {
;     ...
;     else { mn = fmaxf(m_reg, pmax); alpha = __builtin_amdgcn_exp2f((m_reg - mn) * C); m_reg = mn; }
;     float mnC = -mn * C;
; #pragma unroll
;     for (int r = 0; r < 16; ++r) p0[r] = fmaf(p0[r], C, mnC);
; #pragma unroll
;     for (int r = 0; r < 16; ++r) p1[r] = fmaf(p1[r], C, mnC);
; #pragma unroll
;     for (int r = 0; r < 16; ++r) p0[r] = __builtin_amdgcn_exp2f(p0[r]);
; }
; __device__ __forceinline__ void finishSM(f32x16& p0, f32x16& p1, float alpha, float& l_reg, bf16x8& pa0, bf16x8& pa1, bf16x8& pa2, bf16x8& pa3) {
; #pragma unroll
;     for (int r = 0; r < 16; ++r) p1[r] = __builtin_amdgcn_exp2f(p1[r]);
;     float ps = 0;
; #pragma unroll
;     for (int r = 0; r < 16; ++r) ps += p0[r];
; #pragma unroll
;     for (int r = 0; r < 16; ++r) ps += p1[r];
;     { auto rr = __builtin_amdgcn_permlane32_swap(__float_as_uint(ps), __float_as_uint(ps), false, false);
;       ps = __uint_as_float(rr[0]) + __uint_as_float(rr[1]); }
;     l_reg = l_reg * alpha + ps;
;     ...
;     PK4(p0, 0, pa0); PK4(p0, 8, pa1); PK4(p1, 0, pa2); PK4(p1, 8, pa3);
;     ...
; }
; __device__ __forceinline__ void qkt(f32x16& p0, f32x16& p1, const bf16_t* Ks, const bf16x8* qr, int r32, int hi) {
;     p0 = f32x16{}; p1 = f32x16{};
; #pragma unroll
;     for (int d0 = 0; d0 < 8; ++d0) { int cb = (d0 * 16 + hi * 8) * 2;
;         bf16x8 b0 = *reinterpret_cast<const bf16x8*>((const char*)Ks + KSWZ(r32, cb));
;         bf16x8 b1 = *reinterpret_cast<const bf16x8*>((const char*)Ks + KSWZ(32 + r32, cb));
;         p0 = __builtin_amdgcn_mfma_f32_32x32x16_bf16(b0, qr[d0], p0, 0, 0, 0);
;         p1 = __builtin_amdgcn_mfma_f32_32x32x16_bf16(b1, qr[d0], p1, 0, 0, 0); }
	ds_write_b128 v50, v[62:65]
	v_max_f32_e32 v50, 0xf149f2ca, v66
	s_cselect_b64 vcc, -1, 0
	v_cndmask_b32_e32 v166, v50, v198, vcc
	v_sub_f32_e32 v51, 0xf149f2ca, v50
	v_mul_f32_e32 v50, 0xbe0293ee, v166
	v_fmamk_f32 v16, v16, 0x3e0293ee, v50
	v_exp_f32_e32 v163, v16
	v_fmamk_f32 v16, v17, 0x3e0293ee, v50
	v_exp_f32_e32 v177, v16
	v_fmamk_f32 v16, v18, 0x3e0293ee, v50
	v_exp_f32_e32 v164, v16
	v_fmamk_f32 v16, v19, 0x3e0293ee, v50
	v_exp_f32_e32 v229, v16
	v_fmamk_f32 v16, v20, 0x3e0293ee, v50
	v_exp_f32_e32 v176, v16
	v_fmamk_f32 v16, v21, 0x3e0293ee, v50
	v_exp_f32_e32 v230, v16
	v_fmamk_f32 v16, v22, 0x3e0293ee, v50
	v_exp_f32_e32 v165, v16
	v_fmamk_f32 v16, v23, 0x3e0293ee, v50
	v_exp_f32_e32 v175, v16
	v_fmamk_f32 v16, v24, 0x3e0293ee, v50
	v_exp_f32_e32 v171, v16
	v_fmamk_f32 v16, v25, 0x3e0293ee, v50
	v_exp_f32_e32 v173, v16
	v_fmamk_f32 v16, v26, 0x3e0293ee, v50
	v_mul_f32_e32 v51, 0x3e0293ee, v51
	v_exp_f32_e32 v172, v16
	v_fmamk_f32 v16, v27, 0x3e0293ee, v50
	v_exp_f32_e32 v51, v51
	v_exp_f32_e32 v174, v16
	v_fmamk_f32 v16, v28, 0x3e0293ee, v50
	v_exp_f32_e32 v167, v16
	v_fmamk_f32 v16, v29, 0x3e0293ee, v50
	v_exp_f32_e32 v169, v16
	v_fmamk_f32 v16, v30, 0x3e0293ee, v50
	v_mov_b64_e32 v[14:15], s[26:27]
	s_mov_b32 s20, 0x3e0293ee
	v_exp_f32_e32 v168, v16
	v_lshl_add_u64 v[16:17], v[48:49], 0, s[8:9]
	v_pk_fma_f32 v[146:147], v[46:47], s[20:21], v[50:51] op_sel_hi:[1,0,0]
	v_pk_fma_f32 v[148:149], v[44:45], s[20:21], v[50:51] op_sel_hi:[1,0,0]
	v_pk_fma_f32 v[150:151], v[42:43], s[20:21], v[50:51] op_sel_hi:[1,0,0]
	v_pk_fma_f32 v[152:153], v[40:41], s[20:21], v[50:51] op_sel_hi:[1,0,0]
	v_pk_fma_f32 v[154:155], v[38:39], s[20:21], v[50:51] op_sel_hi:[1,0,0]
	v_pk_fma_f32 v[156:157], v[36:37], s[20:21], v[50:51] op_sel_hi:[1,0,0]
	v_pk_fma_f32 v[158:159], v[34:35], s[20:21], v[50:51] op_sel_hi:[1,0,0]
	v_pk_fma_f32 v[160:161], v[32:33], s[20:21], v[50:51] op_sel_hi:[1,0,0]
	v_fmac_f32_e32 v50, 0x3e0293ee, v31
	v_mad_u64_u32 v[18:19], s[8:9], v16, s70, 0
	v_and_b32_e32 v16, 15, v70
	v_exp_f32_e32 v170, v50
	v_lshlrev_b32_e32 v16, 4, v16
	v_mad_i32_i24 v17, v17, s70, v19
	v_or3_b32 v16, v18, s39, v16
	v_cndmask_b32_e64 v225, v51, 1.0, vcc
	v_lshl_add_u64 v[180:181], s[2:3], 0, v[16:17]
	v_mov_b64_e32 v[62:63], v[14:15]
	v_mov_b64_e32 v[46:47], v[14:15]
	v_mov_b64_e32 v[30:31], v[14:15]
	v_cmp_gt_u32_e64 s[6:7], 32, v74
	s_mov_b32 s8, 0x8000
	v_mov_b64_e32 v[60:61], v[12:13]
	v_mov_b64_e32 v[58:59], v[10:11]
	v_mov_b64_e32 v[56:57], v[8:9]
	v_mov_b64_e32 v[54:55], v[6:7]
	v_mov_b64_e32 v[52:53], v[4:5]
	v_mov_b64_e32 v[50:51], v[2:3]
	v_mov_b64_e32 v[48:49], v[0:1]
	v_mov_b64_e32 v[44:45], v[12:13]
	v_mov_b64_e32 v[42:43], v[10:11]
	v_mov_b64_e32 v[40:41], v[8:9]
	v_mov_b64_e32 v[38:39], v[6:7]
	v_mov_b64_e32 v[36:37], v[4:5]
	v_mov_b64_e32 v[34:35], v[2:3]
	v_mov_b64_e32 v[32:33], v[0:1]
	v_mov_b64_e32 v[28:29], v[12:13]
	v_mov_b64_e32 v[26:27], v[10:11]
	v_mov_b64_e32 v[24:25], v[8:9]
	v_mov_b64_e32 v[22:23], v[6:7]
	v_mov_b64_e32 v[20:21], v[4:5]
	v_mov_b64_e32 v[18:19], v[2:3]
	v_mov_b64_e32 v[16:17], v[0:1]
	s_waitcnt lgkmcnt(0)
	s_barrier
.LBB0_269:
	s_mov_b32 s13, s12
	s_mov_b32 s12, s8
	s_add_i32 s8, s37, 0
	v_add_u32_e32 v71, s8, v220
	ds_read_b128 v[64:67], v71 offset:49152
	ds_read_b128 v[68:71], v71 offset:57344
	v_add_u32_e32 v239, s8, v222
	ds_read_b128 v[232:235], v239 offset:49152
	ds_read_b128 v[236:239], v239 offset:57344
	v_add_u32_e32 v247, s8, v221
	ds_read_b128 v[240:243], v247 offset:49152
	ds_read_b128 v[244:247], v247 offset:57344
	s_waitcnt lgkmcnt(5)
	v_mfma_f32_32x32x16_bf16 v[80:95], v[64:67], v[126:129], 0
	v_exp_f32_e32 v160, v160
	v_exp_f32_e32 v161, v161
	v_exp_f32_e32 v158, v158
	v_exp_f32_e32 v159, v159
	v_exp_f32_e32 v156, v156
	v_exp_f32_e32 v157, v157
	s_waitcnt lgkmcnt(4)
	v_mfma_f32_32x32x16_bf16 v[64:79], v[68:71], v[126:129], 0
	v_exp_f32_e32 v154, v154
	v_exp_f32_e32 v155, v155
	v_exp_f32_e32 v152, v152
	v_exp_f32_e32 v153, v153
	v_exp_f32_e32 v150, v150
	v_exp_f32_e32 v151, v151
	s_waitcnt lgkmcnt(3)
	v_mfma_f32_32x32x16_bf16 v[80:95], v[232:235], v[122:125], v[80:95]
	v_exp_f32_e32 v148, v148
	v_exp_f32_e32 v149, v149
	v_exp_f32_e32 v146, v146
	v_exp_f32_e32 v147, v147
	s_waitcnt lgkmcnt(2)
	v_mfma_f32_32x32x16_bf16 v[64:79], v[236:239], v[122:125], v[64:79]
	v_add_u32_e32 v239, s8, v218
	ds_read_b128 v[232:235], v239 offset:49152
	ds_read_b128 v[236:239], v239 offset:57344
	v_add_f32_e32 v162, 0, v163
	v_add_f32_e32 v162, v177, v162
	v_add_f32_e32 v162, v164, v162
	v_add_f32_e32 v162, v229, v162
	v_add_f32_e32 v162, v176, v162
	s_waitcnt lgkmcnt(3)
	v_mfma_f32_32x32x16_bf16 v[80:95], v[240:243], v[118:121], v[80:95]
	v_add_f32_e32 v162, v230, v162
	v_add_f32_e32 v162, v165, v162
	v_add_f32_e32 v162, v175, v162
	v_add_f32_e32 v162, v171, v162
	v_add_f32_e32 v162, v173, v162
	s_waitcnt lgkmcnt(2)
	v_mfma_f32_32x32x16_bf16 v[64:79], v[244:247], v[118:121], v[64:79]
	v_add_u32_e32 v247, s8, v215
	ds_read_b128 v[240:243], v247 offset:49152
	ds_read_b128 v[244:247], v247 offset:57344
	v_add_f32_e32 v162, v172, v162
	v_add_f32_e32 v162, v174, v162
	v_add_f32_e32 v162, v167, v162
	v_add_f32_e32 v162, v169, v162
	v_add_f32_e32 v162, v168, v162
	s_waitcnt lgkmcnt(3)
	v_mfma_f32_32x32x16_bf16 v[80:95], v[232:235], v[114:117], v[80:95]
	v_add_f32_e32 v162, v170, v162
	v_add_f32_e32 v162, v160, v162
	v_add_f32_e32 v162, v161, v162
	v_add_f32_e32 v162, v158, v162
	v_add_f32_e32 v162, v159, v162
	s_waitcnt lgkmcnt(2)
; __device__ __forceinline__ void finishSM(f32x16& p0, f32x16& p1, float alpha, float& l_reg, bf16x8& pa0, bf16x8& pa1, bf16x8& pa2, bf16x8& pa3) {
; #pragma unroll
;     for (int r = 0; r < 16; ++r) p1[r] = __builtin_amdgcn_exp2f(p1[r]);
;     float ps = 0;
; #pragma unroll
;     for (int r = 0; r < 16; ++r) ps += p0[r];
; #pragma unroll
;     for (int r = 0; r < 16; ++r) ps += p1[r];
;     { auto rr = __builtin_amdgcn_permlane32_swap(__float_as_uint(ps), __float_as_uint(ps), false, false);
;       ps = __uint_as_float(rr[0]) + __uint_as_float(rr[1]); }
;     l_reg = l_reg * alpha + ps;
;     ...
;     PK4(p0, 0, pa0); PK4(p0, 8, pa1); PK4(p1, 0, pa2); PK4(p1, 8, pa3);
;     ...
; }
; __device__ __forceinline__ void qkt(f32x16& p0, f32x16& p1, const bf16_t* Ks, const bf16x8* qr, int r32, int hi) {
;     p0 = f32x16{}; p1 = f32x16{};
; #pragma unroll
;     for (int d0 = 0; d0 < 8; ++d0) { int cb = (d0 * 16 + hi * 8) * 2;
;         bf16x8 b0 = *reinterpret_cast<const bf16x8*>((const char*)Ks + KSWZ(r32, cb));
;         bf16x8 b1 = *reinterpret_cast<const bf16x8*>((const char*)Ks + KSWZ(32 + r32, cb));
;         p0 = __builtin_amdgcn_mfma_f32_32x32x16_bf16(b0, qr[d0], p0, 0, 0, 0);
;         p1 = __builtin_amdgcn_mfma_f32_32x32x16_bf16(b1, qr[d0], p1, 0, 0, 0); }
; }
; __device__ __forceinline__ int v_st(int k, int c) { const int kk = (k & ~0xC) | ((k & 4) << 1) | ((k & 8) >> 1); return ((kk >> 3) * 4 + (c >> 5)) * 512 + ((kk & 7) * 32 + (c & 31)) * 2; }
; __device__ __forceinline__ int v_rd_base(int lane) { return ((lane & 3) << 3) | (((lane >> 2) & 3) << 6) | (((lane >> 4) & 1) << 5) | (((lane >> 5) & 1) << 8); }
; template <int OFF> __device__ __forceinline__ s16x4 tr_read(int vb) {
;     s16x4 r; asm volatile("ds_read_b64_tr_b16 %0, %1 offset:%2" : "=&v"(r) : "v"(vb), "i"(OFF) : "memory"); return r;
; }
; template <int D0> __device__ __forceinline__ void pv_one(f32x16& od, int vb, bf16x8 pa0, bf16x8 pa1, bf16x8 pa2, bf16x8 pa3) {
;     const s16x4 l0 = tr_read<v_rd_off(D0, 0, 0)>(vb), h0 = tr_read<v_rd_off(D0, 0, 1)>(vb), l1 = tr_read<v_rd_off(D0, 1, 0)>(vb), h1 = tr_read<v_rd_off(D0, 1, 1)>(vb);
;     const s16x4 l2 = tr_read<v_rd_off(D0, 2, 0)>(vb), h2 = tr_read<v_rd_off(D0, 2, 1)>(vb), l3 = tr_read<v_rd_off(D0, 3, 0)>(vb), h3 = tr_read<v_rd_off(D0, 3, 1)>(vb);
;     asm volatile("s_waitcnt lgkmcnt(0)" ::: "memory"); SBAR();
	v_mfma_f32_32x32x16_bf16 v[64:79], v[236:239], v[114:117], v[64:79]
	v_add_u32_e32 v239, s8, v213
	ds_read_b128 v[232:235], v239 offset:49152
	ds_read_b128 v[236:239], v239 offset:57344
	v_add_f32_e32 v162, v156, v162
	v_add_f32_e32 v162, v157, v162
	v_add_f32_e32 v162, v154, v162
	v_add_f32_e32 v162, v155, v162
	v_add_f32_e32 v162, v152, v162
	s_waitcnt lgkmcnt(3)
	v_mfma_f32_32x32x16_bf16 v[80:95], v[240:243], v[110:113], v[80:95]
	v_add_f32_e32 v162, v153, v162
	v_add_f32_e32 v162, v150, v162
	v_add_f32_e32 v162, v151, v162
	v_add_f32_e32 v162, v148, v162
	v_add_f32_e32 v162, v149, v162
	s_waitcnt lgkmcnt(2)
	v_mfma_f32_32x32x16_bf16 v[64:79], v[244:247], v[110:113], v[64:79]
	v_add_u32_e32 v247, s8, v223
	ds_read_b128 v[240:243], v247 offset:49152
	ds_read_b128 v[244:247], v247 offset:57344
	v_add_f32_e32 v162, v146, v162
	v_add_f32_e32 v226, v147, v162
	v_mov_b32_e32 v227, v226
	v_cvt_pk_bf16_f32 v162, v163, v177
	s_waitcnt lgkmcnt(3)
	v_mfma_f32_32x32x16_bf16 v[80:95], v[232:235], v[106:109], v[80:95]
	v_cvt_pk_bf16_f32 v163, v164, v229
	v_cvt_pk_bf16_f32 v164, v176, v230
	v_cvt_pk_bf16_f32 v165, v165, v175
	v_cvt_pk_bf16_f32 v228, v171, v173
	s_waitcnt lgkmcnt(2)
	v_mfma_f32_32x32x16_bf16 v[64:79], v[236:239], v[106:109], v[64:79]
	v_add_u32_e32 v239, s8, v224
	ds_read_b128 v[232:235], v239 offset:49152
	ds_read_b128 v[236:239], v239 offset:57344
	v_cvt_pk_bf16_f32 v229, v172, v174
	v_cvt_pk_bf16_f32 v230, v167, v169
	v_permlane32_swap_b32_e32 v226, v227
	v_permlane32_swap_b32_e32 v162, v164
	s_waitcnt lgkmcnt(3)
	v_mfma_f32_32x32x16_bf16 v[80:95], v[240:243], v[102:105], v[80:95]
	v_cvt_pk_bf16_f32 v231, v168, v170
	v_permlane32_swap_b32_e32 v228, v230
	v_cvt_pk_bf16_f32 v168, v160, v161
	v_cvt_pk_bf16_f32 v169, v158, v159
	s_waitcnt lgkmcnt(2)
	v_mfma_f32_32x32x16_bf16 v[64:79], v[244:247], v[102:105], v[64:79]
	v_cvt_pk_bf16_f32 v170, v156, v157
	v_cvt_pk_bf16_f32 v171, v154, v155
	v_cvt_pk_bf16_f32 v172, v152, v153
	v_cvt_pk_bf16_f32 v173, v150, v151
	s_waitcnt lgkmcnt(1)
	v_mfma_f32_32x32x16_bf16 v[80:95], v[232:235], v[98:101], v[80:95]
	v_cvt_pk_bf16_f32 v174, v148, v149
	v_cvt_pk_bf16_f32 v175, v146, v147
	v_permlane32_swap_b32_e32 v163, v165
	v_permlane32_swap_b32_e32 v229, v231
	s_waitcnt lgkmcnt(0)
	v_mfma_f32_32x32x16_bf16 v[64:79], v[236:239], v[98:101], v[64:79]
	v_permlane32_swap_b32_e32 v168, v170
	v_permlane32_swap_b32_e32 v169, v171
	v_permlane32_swap_b32_e32 v172, v174
	v_permlane32_swap_b32_e32 v173, v175
	s_mov_b32 s8, 0xfffb8000
	v_add_co_u32_e32 v150, vcc, s8, v180
	s_mov_b32 s8, 0xfffd0000
	s_nop 0
	v_addc_co_u32_e32 v151, vcc, -1, v181, vcc
	v_add_co_u32_e32 v154, vcc, s8, v180
	s_nop 1
	v_addc_co_u32_e32 v155, vcc, -1, v181, vcc
	global_load_dwordx4 v[146:149], v[150:151], off
	s_nop 0
	global_load_dwordx4 v[150:153], v[150:151], off offset:-512
	s_nop 0
	global_load_dwordx4 v[158:161], v[154:155], off
	s_nop 0
	global_load_dwordx4 v[154:157], v[154:155], off offset:-512
	v_add_u32_e32 v211, s13, v212
	ds_read_b64_tr_b16 v[232:233], v211 offset:0
	ds_read_b64_tr_b16 v[234:235], v211 offset:0x800
	ds_read_b64_tr_b16 v[236:237], v211 offset:0x1000
	ds_read_b64_tr_b16 v[238:239], v211 offset:0x1800
	ds_read_b64_tr_b16 v[240:241], v211 offset:0x2000
	ds_read_b64_tr_b16 v[242:243], v211 offset:0x2800
	ds_read_b64_tr_b16 v[244:245], v211 offset:0x3000
	ds_read_b64_tr_b16 v[246:247], v211 offset:0x3800
	s_waitcnt lgkmcnt(0)
	s_nop 0
	v_mfma_f32_32x32x16_bf16 v[0:15], v[162:165], v[232:235], v[0:15]
	ds_read_b64_tr_b16 v[232:233], v211 offset:0x200
	ds_read_b64_tr_b16 v[234:235], v211 offset:0xa00
	v_mfma_f32_32x32x16_bf16 v[0:15], v[228:231], v[236:239], v[0:15]
	ds_read_b64_tr_b16 v[236:237], v211 offset:0x1200
	ds_read_b64_tr_b16 v[238:239], v211 offset:0x1a00
	v_mfma_f32_32x32x16_bf16 v[0:15], v[168:171], v[240:243], v[0:15]
	ds_read_b64_tr_b16 v[240:241], v211 offset:0x2200
	ds_read_b64_tr_b16 v[242:243], v211 offset:0x2a00
	v_mfma_f32_32x32x16_bf16 v[0:15], v[172:175], v[244:247], v[0:15]
	ds_read_b64_tr_b16 v[244:245], v211 offset:0x3200
	ds_read_b64_tr_b16 v[246:247], v211 offset:0x3a00
	s_waitcnt lgkmcnt(0)
	v_mfma_f32_32x32x16_bf16 v[48:63], v[162:165], v[232:235], v[48:63]
	ds_read_b64_tr_b16 v[232:233], v211 offset:0x400
	ds_read_b64_tr_b16 v[234:235], v211 offset:0xc00
	v_mfma_f32_32x32x16_bf16 v[48:63], v[228:231], v[236:239], v[48:63]
	ds_read_b64_tr_b16 v[236:237], v211 offset:0x1400
	ds_read_b64_tr_b16 v[238:239], v211 offset:0x1c00
	v_mfma_f32_32x32x16_bf16 v[48:63], v[168:171], v[240:243], v[48:63]
	ds_read_b64_tr_b16 v[240:241], v211 offset:0x2400
	ds_read_b64_tr_b16 v[242:243], v211 offset:0x2c00
	v_mfma_f32_32x32x16_bf16 v[48:63], v[172:175], v[244:247], v[48:63]
	ds_read_b64_tr_b16 v[244:245], v211 offset:0x3400
	ds_read_b64_tr_b16 v[246:247], v211 offset:0x3c00
	s_waitcnt lgkmcnt(0)
	v_mfma_f32_32x32x16_bf16 v[32:47], v[162:165], v[232:235], v[32:47]
	ds_read_b64_tr_b16 v[232:233], v211 offset:0x600
	ds_read_b64_tr_b16 v[234:235], v211 offset:0xe00
	v_mfma_f32_32x32x16_bf16 v[32:47], v[228:231], v[236:239], v[32:47]
	ds_read_b64_tr_b16 v[236:237], v211 offset:0x1600
	ds_read_b64_tr_b16 v[238:239], v211 offset:0x1e00
	v_mfma_f32_32x32x16_bf16 v[32:47], v[168:171], v[240:243], v[32:47]
	ds_read_b64_tr_b16 v[240:241], v211 offset:0x2600
	ds_read_b64_tr_b16 v[242:243], v211 offset:0x2e00
	v_mfma_f32_32x32x16_bf16 v[32:47], v[172:175], v[244:247], v[32:47]
	ds_read_b64_tr_b16 v[244:245], v211 offset:0x3600
	ds_read_b64_tr_b16 v[246:247], v211 offset:0x3e00
	s_waitcnt lgkmcnt(0)
; #define SBAR() __builtin_amdgcn_sched_barrier(0)
; #define SWAIT() asm volatile("s_waitcnt vmcnt(4)" ::: "memory")
; __device__ __forceinline__ void partialSM(f32x16& p0, f32x16& p1, float& m_reg, float& mn, float& alpha) {
;     constexpr float C = SCALE * 1.4426950408889634f;
;     float pmax = p0[0];
; #pragma unroll
;     for (int r = 1; r < 16; ++r) pmax = fmaxf(pmax, p0[r]);
; #pragma unroll
;     for (int r = 0; r < 16; ++r) pmax = fmaxf(pmax, p1[r]);
;     { auto rr = __builtin_amdgcn_permlane32_swap(__float_as_uint(pmax), __float_as_uint(pmax), false, false);
;       pmax = fmaxf(__uint_as_float(rr[0]), __uint_as_float(rr[1])); }
;     if (__builtin_expect(__all(pmax - m_reg <= THR / SCALE), 1)) { mn = m_reg; alpha = 1.f; }
;     else { mn = fmaxf(m_reg, pmax); alpha = __builtin_amdgcn_exp2f((m_reg - mn) * C); m_reg = mn; }
;     float mnC = -mn * C;
; #pragma unroll
;     for (int r = 0; r < 16; ++r) p0[r] = fmaf(p0[r], C, mnC);
; #pragma unroll
;     for (int r = 0; r < 16; ++r) p1[r] = fmaf(p1[r], C, mnC);
; #pragma unroll
;     for (int r = 0; r < 16; ++r) p0[r] = __builtin_amdgcn_exp2f(p0[r]);
; __device__ __forceinline__ void attn_dense_body(const bf16_t* __restrict__ Qb, const bf16_t* __restrict__ Kh, const bf16_t* __restrict__ Vh,
;                                                 bf16_t* __restrict__ Ob, int seq, char* lds, int dry) {
;     ...
;     f32x16 pA0, pA1, pB0, pB1; float mnA, mnB, alA, alB; bf16x8 pa0, pa1, pa2, pa3; const int NT = seq / KVBLK;
;     SLOAD(0, 0); asm volatile("s_waitcnt vmcnt(0)" ::: "memory"); SWRITE(0, 0); __syncthreads();
;     qkt(pA0, pA1, K_lds, qr, r32, hi); partialSM(pA0, pA1, m_reg, mnA, alA);
;     SLOAD(1, KVBLK); if (2 < NT) SLOAD(0, 2 * KVBLK);
;     SWAIT(); SWRITE((int)SHM_K, 1); __syncthreads();
;     int oq = (int)SHM_K, ov = 0, ow = 2 * (int)SHM_K;
;     for (int j = 1; j + 1 < NT; j += 2) {
;         SBAR(); qkt(pB0, pB1, (bf16_t*)((char*)K_lds + oq), qr, r32, hi);
;         finishSM(pA0, pA1, alA, l_reg, pa0, pa1, pa2, pa3); SBAR();
;         SLOAD(1, (j + 2) * KVBLK); SBAR();
;         pv_d0(o, vb0 + ov, pa0, pa1, pa2, pa3); partialSM(pB0, pB1, m_reg, mnB, alB);
;         SWAIT(); SWRITE(ow, 0);
;         RESC(alB); __syncthreads();
	v_mfma_f32_32x32x16_bf16 v[16:31], v[162:165], v[232:235], v[16:31]
	v_max_f32_e32 v162, v81, v81
	v_max_f32_e32 v163, v80, v80
	v_max_f32_e32 v162, v163, v162
	v_max3_f32 v162, v162, v82, v83
	v_max3_f32 v162, v162, v84, v85
	v_max3_f32 v162, v162, v86, v87
	v_max3_f32 v162, v162, v88, v89
	v_max3_f32 v162, v162, v90, v91
	v_max3_f32 v162, v162, v92, v93
	v_max3_f32 v162, v162, v94, v95
	v_max3_f32 v162, v162, v64, v65
	v_mfma_f32_32x32x16_bf16 v[16:31], v[228:231], v[236:239], v[16:31]
	v_max3_f32 v162, v162, v66, v67
	v_max3_f32 v162, v162, v68, v69
	v_max3_f32 v162, v162, v70, v71
	v_max3_f32 v162, v162, v72, v73
	v_max3_f32 v162, v162, v74, v75
	v_max3_f32 v162, v162, v76, v77
	v_max3_f32 v162, v162, v78, v79
	v_mov_b32_e32 v163, v162
	v_mfma_f32_32x32x16_bf16 v[16:31], v[168:171], v[240:243], v[16:31]
	s_nop 0
	v_permlane32_swap_b32_e32 v162, v163
	v_max_f32_e32 v163, v163, v163
	v_max_f32_e32 v162, v162, v162
	v_max_f32_e32 v162, v162, v163
	v_sub_f32_e32 v163, v162, v166
	v_cmp_ge_f32_e32 vcc, s72, v163
	v_max_f32_e32 v163, v166, v166
	v_max_f32_e32 v162, v163, v162
	v_sub_f32_e32 v163, v166, v162
	v_mul_f32_e32 v163, 0x3e0293ee, v163
	v_mfma_f32_32x32x16_bf16 v[16:31], v[172:175], v[244:247], v[16:31]
	v_exp_f32_e32 v163, v163
	s_cmp_eq_u64 vcc, exec
	s_cselect_b64 s[8:9], -1, 0
	s_add_i32 s14, s12, 0
	v_cndmask_b32_e64 v228, v163, 1.0, s[8:9]
	v_add_u32_e32 v163, s14, v216
	s_waitcnt vmcnt(4)
	s_waitcnt vmcnt(4)
	ds_write_b128 v163, v[134:137]
	v_add_u32_e32 v163, s14, v217
	ds_write_b128 v163, v[142:145]
	v_add_u32_e32 v163, s14, v214
	ds_write_b128 v163, v[138:141] offset:49152
	v_add_u32_e32 v163, s14, v219
	v_cmp_gt_f32_e32 vcc, 1.0, v228
	ds_write_b128 v163, v[130:133] offset:49152
	s_cbranch_vccz .LBB0_273
	s_and_saveexec_b64 s[10:11], s[6:7]
	ds_write_b32 v209, v228 offset:128
	s_or_b64 exec, exec, s[10:11]
	s_waitcnt lgkmcnt(0)
	v_add_u32_e32 v163, v179, v96
	ds_read_b128 v[168:171], v163 offset:224
	ds_read_b128 v[172:175], v163 offset:192
	ds_read_b128 v[230:233], v163 offset:160
	ds_read_b128 v[234:237], v163 offset:128
	s_waitcnt lgkmcnt(3)
	v_pk_mul_f32 v[12:13], v[12:13], v[168:169]
	s_waitcnt lgkmcnt(2)
	v_pk_mul_f32 v[8:9], v[8:9], v[172:173]
	s_waitcnt lgkmcnt(1)
	v_pk_mul_f32 v[4:5], v[4:5], v[230:231]
	v_pk_mul_f32 v[14:15], v[14:15], v[170:171]
	v_pk_mul_f32 v[10:11], v[10:11], v[174:175]
	v_pk_mul_f32 v[6:7], v[6:7], v[232:233]
	s_waitcnt lgkmcnt(0)
	v_pk_mul_f32 v[2:3], v[2:3], v[236:237]
	v_pk_mul_f32 v[0:1], v[0:1], v[234:235]
	v_pk_mul_f32 v[60:61], v[60:61], v[168:169]
	v_pk_mul_f32 v[56:57], v[56:57], v[172:173]
	v_pk_mul_f32 v[52:53], v[52:53], v[230:231]
	v_pk_mul_f32 v[62:63], v[62:63], v[170:171]
	v_pk_mul_f32 v[58:59], v[58:59], v[174:175]
	v_pk_mul_f32 v[54:55], v[54:55], v[232:233]
	v_pk_mul_f32 v[50:51], v[50:51], v[236:237]
	v_pk_mul_f32 v[48:49], v[48:49], v[234:235]
	v_pk_mul_f32 v[44:45], v[44:45], v[168:169]
	v_pk_mul_f32 v[40:41], v[40:41], v[172:173]
	v_pk_mul_f32 v[36:37], v[36:37], v[230:231]
	v_pk_mul_f32 v[46:47], v[46:47], v[170:171]
	v_pk_mul_f32 v[42:43], v[42:43], v[174:175]
	v_pk_mul_f32 v[38:39], v[38:39], v[232:233]
	v_pk_mul_f32 v[34:35], v[34:35], v[236:237]
	v_pk_mul_f32 v[32:33], v[32:33], v[234:235]
	v_pk_mul_f32 v[28:29], v[28:29], v[168:169]
	v_pk_mul_f32 v[24:25], v[24:25], v[172:173]
	v_pk_mul_f32 v[20:21], v[20:21], v[230:231]
	v_pk_mul_f32 v[30:31], v[30:31], v[170:171]
	v_pk_mul_f32 v[26:27], v[26:27], v[174:175]
	v_pk_mul_f32 v[22:23], v[22:23], v[232:233]
	v_pk_mul_f32 v[18:19], v[18:19], v[236:237]
	v_pk_mul_f32 v[16:17], v[16:17], v[234:235]
.LBB0_273:
	v_cndmask_b32_e64 v229, v162, v166, s[8:9]
	v_mul_f32_e32 v170, 0xbe0293ee, v229
	v_fmamk_f32 v80, v80, 0x3e0293ee, v170
	v_fmamk_f32 v81, v81, 0x3e0293ee, v170
	v_fmamk_f32 v82, v82, 0x3e0293ee, v170
	v_fmamk_f32 v83, v83, 0x3e0293ee, v170
	v_fmamk_f32 v84, v84, 0x3e0293ee, v170
	v_fmamk_f32 v85, v85, 0x3e0293ee, v170
	v_fmamk_f32 v86, v86, 0x3e0293ee, v170
	v_fmamk_f32 v87, v87, 0x3e0293ee, v170
	v_fmamk_f32 v88, v88, 0x3e0293ee, v170
	v_fmamk_f32 v89, v89, 0x3e0293ee, v170
	v_fmamk_f32 v90, v90, 0x3e0293ee, v170
	v_fmamk_f32 v91, v91, 0x3e0293ee, v170
	v_fmamk_f32 v92, v92, 0x3e0293ee, v170
	v_fmamk_f32 v93, v93, 0x3e0293ee, v170
	v_fmamk_f32 v94, v94, 0x3e0293ee, v170
	v_fmamk_f32 v95, v95, 0x3e0293ee, v170
	v_fmamk_f32 v171, v64, 0x3e0293ee, v170
	v_fmamk_f32 v172, v65, 0x3e0293ee, v170
	v_fmamk_f32 v173, v66, 0x3e0293ee, v170
	v_fmamk_f32 v174, v67, 0x3e0293ee, v170
	v_fmamk_f32 v175, v68, 0x3e0293ee, v170
	v_fmamk_f32 v176, v69, 0x3e0293ee, v170
	v_fmamk_f32 v177, v70, 0x3e0293ee, v170
	v_fmamk_f32 v230, v71, 0x3e0293ee, v170
	v_fmamk_f32 v231, v72, 0x3e0293ee, v170
	v_fmamk_f32 v232, v73, 0x3e0293ee, v170
	v_fmamk_f32 v233, v74, 0x3e0293ee, v170
	v_fmamk_f32 v234, v75, 0x3e0293ee, v170
	v_fmamk_f32 v235, v76, 0x3e0293ee, v170
	v_fmamk_f32 v236, v77, 0x3e0293ee, v170
	v_fmamk_f32 v237, v78, 0x3e0293ee, v170
	v_fmac_f32_e32 v170, 0x3e0293ee, v79
	v_exp_f32_e32 v238, v80
	v_exp_f32_e32 v239, v81
	v_exp_f32_e32 v240, v82
	v_exp_f32_e32 v241, v83
	v_exp_f32_e32 v242, v84
	v_exp_f32_e32 v243, v85
	v_exp_f32_e32 v244, v86
	v_exp_f32_e32 v245, v87
	v_exp_f32_e32 v246, v88
	v_exp_f32_e32 v247, v89
	v_exp_f32_e32 v248, v90
	v_exp_f32_e32 v249, v91
	v_exp_f32_e32 v250, v92
	v_exp_f32_e32 v251, v93
	v_exp_f32_e32 v252, v94
	v_exp_f32_e32 v253, v95
	s_waitcnt lgkmcnt(0)
	s_barrier
; #define SBAR() __builtin_amdgcn_sched_barrier(0)
; #define SLOAD(i, k0) do { sv0[i] = *(const bf16x8*)(&Vh[(long)((k0) + sr) * LDK + sc]); sv1[i] = *(const bf16x8*)(&Vh[(long)((k0) + 32 + sr) * LDK + sc]); \
;     sk0[i] = *(const bf16x8*)(&Kh[(long)((k0) + sr) * LDK + sc]); sk1[i] = *(const bf16x8*)(&Kh[(long)((k0) + 32 + sr) * LDK + sc]); } while (0)
; __device__ __forceinline__ void finishSM(f32x16& p0, f32x16& p1, float alpha, float& l_reg, bf16x8& pa0, bf16x8& pa1, bf16x8& pa2, bf16x8& pa3) {
; #pragma unroll
;     for (int r = 0; r < 16; ++r) p1[r] = __builtin_amdgcn_exp2f(p1[r]);
;     float ps = 0;
; #pragma unroll
;     for (int r = 0; r < 16; ++r) ps += p0[r];
; #pragma unroll
;     for (int r = 0; r < 16; ++r) ps += p1[r];
;     { auto rr = __builtin_amdgcn_permlane32_swap(__float_as_uint(ps), __float_as_uint(ps), false, false);
;       ps = __uint_as_float(rr[0]) + __uint_as_float(rr[1]); }
;     l_reg = l_reg * alpha + ps;
;     ...
;     PK4(p0, 0, pa0); PK4(p0, 8, pa1); PK4(p1, 0, pa2); PK4(p1, 8, pa3);
;     ...
; }
; __device__ __forceinline__ void qkt(f32x16& p0, f32x16& p1, const bf16_t* Ks, const bf16x8* qr, int r32, int hi) {
;     p0 = f32x16{}; p1 = f32x16{};
; #pragma unroll
;     for (int d0 = 0; d0 < 8; ++d0) { int cb = (d0 * 16 + hi * 8) * 2;
;         bf16x8 b0 = *reinterpret_cast<const bf16x8*>((const char*)Ks + KSWZ(r32, cb));
;         bf16x8 b1 = *reinterpret_cast<const bf16x8*>((const char*)Ks + KSWZ(32 + r32, cb));
;         p0 = __builtin_amdgcn_mfma_f32_32x32x16_bf16(b0, qr[d0], p0, 0, 0, 0);
;         p1 = __builtin_amdgcn_mfma_f32_32x32x16_bf16(b1, qr[d0], p1, 0, 0, 0); }
; __device__ __forceinline__ void attn_dense_body(const bf16_t* __restrict__ Qb, const bf16_t* __restrict__ Kh, const bf16_t* __restrict__ Vh,
;                                                 bf16_t* __restrict__ Ob, int seq, char* lds, int dry) {
;     ...
;         SBAR(); qkt(pA0, pA1, (bf16_t*)((char*)K_lds + oq), qr, r32, hi);
;         finishSM(pB0, pB1, alB, l_reg, pa0, pa1, pa2, pa3); SBAR();
;         if (j + 3 < NT) SLOAD(0, (j + 3) * KVBLK); SBAR();
	v_add_u32_e32 v71, s14, v220
	ds_read_b128 v[64:67], v71 offset:49152
	ds_read_b128 v[68:71], v71 offset:57344
	v_add_u32_e32 v137, s14, v222
	ds_read_b128 v[130:133], v137 offset:49152
	ds_read_b128 v[134:137], v137 offset:57344
	v_add_u32_e32 v145, s14, v221
	ds_read_b128 v[138:141], v145 offset:49152
	ds_read_b128 v[142:145], v145 offset:57344
	s_waitcnt lgkmcnt(5)
	v_mfma_f32_32x32x16_bf16 v[80:95], v[64:67], v[126:129], 0
	v_exp_f32_e32 v171, v171
	v_exp_f32_e32 v172, v172
	v_exp_f32_e32 v173, v173
	v_exp_f32_e32 v174, v174
	v_exp_f32_e32 v175, v175
	v_exp_f32_e32 v176, v176
	s_waitcnt lgkmcnt(4)
	v_mfma_f32_32x32x16_bf16 v[64:79], v[68:71], v[126:129], 0
	v_exp_f32_e32 v177, v177
	v_exp_f32_e32 v230, v230
	v_exp_f32_e32 v188, v231
	v_exp_f32_e32 v186, v232
	v_exp_f32_e32 v233, v233
	v_exp_f32_e32 v234, v234
	s_waitcnt lgkmcnt(3)
	v_mfma_f32_32x32x16_bf16 v[80:95], v[130:133], v[122:125], v[80:95]
	v_exp_f32_e32 v235, v235
	v_exp_f32_e32 v236, v236
	v_exp_f32_e32 v237, v237
	v_exp_f32_e32 v194, v170
	s_waitcnt lgkmcnt(2)
	v_mfma_f32_32x32x16_bf16 v[64:79], v[134:137], v[122:125], v[64:79]
	v_add_u32_e32 v137, s14, v218
	ds_read_b128 v[130:133], v137 offset:49152
	ds_read_b128 v[134:137], v137 offset:57344
	v_add_f32_e32 v162, 0, v238
	v_add_f32_e32 v162, v239, v162
	v_add_f32_e32 v162, v240, v162
	v_add_f32_e32 v162, v241, v162
	v_add_f32_e32 v162, v242, v162
	s_waitcnt lgkmcnt(3)
	v_mfma_f32_32x32x16_bf16 v[80:95], v[138:141], v[118:121], v[80:95]
	v_add_f32_e32 v162, v243, v162
	v_add_f32_e32 v162, v244, v162
	v_add_f32_e32 v162, v245, v162
	v_add_f32_e32 v162, v246, v162
	v_add_f32_e32 v162, v247, v162
	s_waitcnt lgkmcnt(2)
	v_mfma_f32_32x32x16_bf16 v[64:79], v[142:145], v[118:121], v[64:79]
	v_add_u32_e32 v145, s14, v215
	ds_read_b128 v[138:141], v145 offset:49152
	ds_read_b128 v[142:145], v145 offset:57344
	v_add_f32_e32 v162, v248, v162
	v_add_f32_e32 v162, v249, v162
	v_add_f32_e32 v162, v250, v162
	v_add_f32_e32 v162, v251, v162
	v_add_f32_e32 v162, v252, v162
	s_waitcnt lgkmcnt(3)
	v_mfma_f32_32x32x16_bf16 v[80:95], v[130:133], v[114:117], v[80:95]
	v_add_f32_e32 v162, v253, v162
	v_add_f32_e32 v162, v171, v162
	v_add_f32_e32 v162, v172, v162
	v_add_f32_e32 v162, v173, v162
	v_add_f32_e32 v162, v174, v162
	s_waitcnt lgkmcnt(2)
	v_mfma_f32_32x32x16_bf16 v[64:79], v[134:137], v[114:117], v[64:79]
	v_add_u32_e32 v137, s14, v213
	ds_read_b128 v[130:133], v137 offset:49152
	ds_read_b128 v[134:137], v137 offset:57344
	v_add_f32_e32 v162, v175, v162
	v_add_f32_e32 v162, v176, v162
	v_add_f32_e32 v162, v177, v162
	v_add_f32_e32 v162, v230, v162
	v_add_f32_e32 v162, v188, v162
	s_waitcnt lgkmcnt(3)
	v_mfma_f32_32x32x16_bf16 v[80:95], v[138:141], v[110:113], v[80:95]
	v_add_f32_e32 v162, v186, v162
	v_add_f32_e32 v162, v233, v162
	v_add_f32_e32 v162, v234, v162
	v_add_f32_e32 v162, v235, v162
	v_add_f32_e32 v162, v236, v162
	s_waitcnt lgkmcnt(2)
	v_mfma_f32_32x32x16_bf16 v[64:79], v[142:145], v[110:113], v[64:79]
	v_add_u32_e32 v145, s14, v223
	ds_read_b128 v[138:141], v145 offset:49152
	ds_read_b128 v[142:145], v145 offset:57344
	v_add_f32_e32 v162, v237, v162
	v_add_f32_e32 v231, v194, v162
	v_mov_b32_e32 v232, v231
	v_cvt_pk_bf16_f32 v162, v238, v239
	v_cvt_pk_bf16_f32 v163, v240, v241
	s_waitcnt lgkmcnt(3)
	v_mfma_f32_32x32x16_bf16 v[80:95], v[130:133], v[106:109], v[80:95]
	v_cvt_pk_bf16_f32 v164, v242, v243
	v_cvt_pk_bf16_f32 v165, v244, v245
	v_cvt_pk_bf16_f32 v166, v246, v247
	v_cvt_pk_bf16_f32 v167, v248, v249
	s_waitcnt lgkmcnt(2)
	v_mfma_f32_32x32x16_bf16 v[64:79], v[134:137], v[106:109], v[64:79]
	v_add_u32_e32 v137, s14, v224
	ds_read_b128 v[130:133], v137 offset:49152
	ds_read_b128 v[134:137], v137 offset:57344
	v_cvt_pk_bf16_f32 v168, v250, v251
	v_cvt_pk_bf16_f32 v169, v252, v253
	v_cvt_pk_bf16_f32 v170, v171, v172
	v_cvt_pk_bf16_f32 v171, v173, v174
	s_waitcnt lgkmcnt(3)
	v_mfma_f32_32x32x16_bf16 v[80:95], v[138:141], v[102:105], v[80:95]
	v_cvt_pk_bf16_f32 v172, v175, v176
	v_cvt_pk_bf16_f32 v173, v177, v230
	v_cvt_pk_bf16_f32 v174, v188, v186
	v_cvt_pk_bf16_f32 v175, v233, v234
	s_waitcnt lgkmcnt(2)
	v_mfma_f32_32x32x16_bf16 v[64:79], v[142:145], v[102:105], v[64:79]
	v_cvt_pk_bf16_f32 v176, v235, v236
	v_cvt_pk_bf16_f32 v177, v237, v194
	s_nop 1
	v_permlane32_swap_b32_e32 v231, v232
	s_waitcnt lgkmcnt(1)
	v_mfma_f32_32x32x16_bf16 v[80:95], v[130:133], v[98:101], v[80:95]
	v_permlane32_swap_b32_e32 v162, v164
	v_permlane32_swap_b32_e32 v163, v165
	v_permlane32_swap_b32_e32 v166, v168
	v_permlane32_swap_b32_e32 v167, v169
	s_waitcnt lgkmcnt(0)
	v_mfma_f32_32x32x16_bf16 v[64:79], v[134:137], v[98:101], v[64:79]
	v_permlane32_swap_b32_e32 v170, v172
	v_permlane32_swap_b32_e32 v171, v173
	v_permlane32_swap_b32_e32 v174, v176
	v_permlane32_swap_b32_e32 v175, v177
	s_add_i32 s38, s38, 2
	s_cmp_ge_u32 s38, s36
	s_cselect_b64 s[10:11], -1, 0
	s_and_b64 vcc, exec, s[10:11]
	s_cbranch_vccnz .LBB0_275
	v_add_co_u32_e32 v130, vcc, 0xfffe8000, v180
	s_nop 1
	v_addc_co_u32_e32 v131, vcc, -1, v181, vcc
	global_load_dwordx4 v[134:137], v[130:131], off
	global_load_dwordx4 v[138:141], v[130:131], off offset:-512
	global_load_dwordx4 v[142:145], v[180:181], off
	s_nop 0
	global_load_dwordx4 v[130:133], v[180:181], off offset:-512

; __device__ __forceinline__ void phase_dilated(PP p, int chunk, int dry, unsigned char* lds_g) {
;     ...
;     for (int bt = b0; bt < NTASK; bt += G, ++it) {
;         const int buf = it & 1;
;         asm volatile("s_waitcnt vmcnt(0)" ::: "memory"); __builtin_amdgcn_s_barrier(); asm volatile("" ::: "memory");
.LBB0_319:
	v_readlane_b32 s6, v254, 0
	s_add_i32 s25, s26, s6
	s_cmp_lt_u32 s24, 2
	s_cbranch_scc1 .Lmy_dil_full
	s_and_b64 vcc, exec, s[2:3]
	s_cbranch_vccnz .Lmy_dil_full
	s_waitcnt vmcnt(3)
	s_branch .Lmy_dil_join

; #define DIL_QROW(bt_) (QK3 + ((bt_) >> 11) * 2048 + (((bt_) & 2047) >> 7) * 64 + (size_t)(DIL_BLK(bt_) * 128 + wid * 16 + fr) * LDB_QK)
; __device__ __forceinline__ void phase_dilated(PP p, int chunk, int dry, unsigned char* lds_g) {
;     ...
;         asm volatile("s_waitcnt vmcnt(0)" ::: "memory"); __builtin_amdgcn_s_barrier(); asm volatile("" ::: "memory");
;         const int g = bt >> 11, rem = bt & 2047, h = rem >> 7, blk = DIL_BLK(rem);
;         const int L = 1 << (log2S - 2 * g);
;         const int p0 = blk * 128 + wid * 16;
;         const int u0b = (blk * 128) & (L - 1);
;         bf16x8 qn0 = q0, qn1 = q1;
;         if (bt + G < NTASK) { const bf16_t* qr = DIL_QROW(bt + G); qn0 = *(const bf16x8*)(qr + 8 * fq); qn1 = *(const bf16x8*)(qr + 8 * fq + 32); }
;         if (bt + G < NTASK) DIL_FILL(bt + G, buf ^ 1);
.Lmy_dil_join:
	s_cmpk_lt_i32 s25, 0x1800
	s_barrier
	s_cselect_b64 s[6:7], -1, 0
	s_cmpk_gt_i32 s25, 0x17ff
	s_cselect_b64 s[10:11], -1, 0
	s_and_b64 vcc, exec, s[10:11]
	v_lshlrev_b32_e32 v96, 1, v52
	s_cbranch_vccnz .LBB0_321
	s_and_b32 s8, s25, 0xfffff800
	s_ashr_i32 s9, s8, 31
	s_lshl_b64 s[8:9], s[8:9], 1
	s_add_u32 s8, s15, s8
	s_addc_u32 s9, s16, s9
	s_and_b32 s12, s25, 0x780
	s_add_u32 s8, s8, s12
	s_addc_u32 s9, s9, 0
	s_add_i32 s12, s64, s21
	s_and_b32 s12, s12, 0x70
	s_bfe_u32 s13, s25, 0x40003
	s_or_b32 s12, s12, s13
	v_lshl_add_u32 v26, s12, 7, v51
	v_mov_b64_e32 v[24:25], s[8:9]
	v_mad_i64_i32 v[24:25], s[8:9], v26, s77, v[24:25]
	v_lshl_add_u64 v[24:25], v[24:25], 0, v[96:97]
	global_load_dwordx4 v[28:31], v[24:25], off
	s_nop 0
	global_load_dwordx4 v[24:27], v[24:25], off offset:64

; __device__ __forceinline__ unsigned cvt_pk_bf16(float lo, float hi) { unsigned r; asm volatile("v_cvt_pk_bf16_f32 %0, %1, %2" : "=v"(r) : "v"(lo), "v"(hi)); return r; }
; __device__ __forceinline__ void phase_dilated(PP p, int chunk, int dry, unsigned char* lds_g) {
;     ...
;         l += __shfl_xor(l, 16); l += __shfl_xor(l, 32);
;         const float rl = 1.f / l;
;         if (fq == 0 && !dry) lse[((size_t)g * 16384 + p0 + fr) * 16 + h] = mx + __log2f(l);
;         u32x4 w0, w1;
;         w0.x = cvt_pk_bf16(o[0][0] * rl, o[0][1] * rl); w0.y = cvt_pk_bf16(o[0][2] * rl, o[0][3] * rl); w0.z = cvt_pk_bf16(o[1][0] * rl, o[1][1] * rl); w0.w = cvt_pk_bf16(o[1][2] * rl, o[1][3] * rl);
;         w1.x = cvt_pk_bf16(o[2][0] * rl, o[2][1] * rl); w1.y = cvt_pk_bf16(o[2][2] * rl, o[2][3] * rl); w1.z = cvt_pk_bf16(o[3][0] * rl, o[3][1] * rl); w1.w = cvt_pk_bf16(o[3][2] * rl, o[3][3] * rl);
;         pw0 = w0; pw1 = w1; q0 = qn0; q1 = qn1;
.LBB0_327:
	s_or_b64 exec, exec, s[6:7]
	v_div_scale_f32 v57, s[6:7], v55, v55, 1.0
	v_rcp_f32_e32 v63, v57
	v_div_scale_f32 v64, vcc, 1.0, v55, 1.0
	s_add_i32 s24, s24, 1
	v_fma_f32 v65, -v57, v63, 1.0
	v_fmac_f32_e32 v63, v65, v63
	v_mul_f32_e32 v65, v64, v63
	v_fma_f32 v66, -v57, v65, v64
	v_fmac_f32_e32 v65, v66, v63
	v_fma_f32 v57, -v57, v65, v64
	v_div_fmas_f32 v57, v57, v63, v65
	v_div_fixup_f32 v55, v57, v55, 1.0
	v_mul_f32_e32 v40, v40, v55
	v_mul_f32_e32 v41, v41, v55
	v_cvt_pk_bf16_f32 v40, v40, v41
	v_mul_f32_e32 v41, v42, v55
	v_mul_f32_e32 v42, v43, v55
	v_cvt_pk_bf16_f32 v41, v41, v42
	v_mul_f32_e32 v42, v44, v55
	v_mul_f32_e32 v43, v45, v55
	v_cvt_pk_bf16_f32 v42, v42, v43
	v_mul_f32_e32 v43, v46, v55
	v_mul_f32_e32 v44, v47, v55
	v_mul_f32_e32 v36, v36, v55
	v_mul_f32_e32 v37, v37, v55
	v_mul_f32_e32 v32, v32, v55
	v_mul_f32_e32 v33, v33, v55
	s_add_i32 s21, s21, s64
	s_and_b64 vcc, exec, s[10:11]
	v_cvt_pk_bf16_f32 v43, v43, v44
	v_cvt_pk_bf16_f32 v44, v36, v37
	v_mul_f32_e32 v36, v38, v55
	v_mul_f32_e32 v37, v39, v55
	v_cvt_pk_bf16_f32 v45, v36, v37
	v_cvt_pk_bf16_f32 v46, v32, v33
	v_mul_f32_e32 v32, v34, v55
	v_mul_f32_e32 v33, v35, v55
	v_cvt_pk_bf16_f32 v47, v32, v33
	s_cbranch_vccnz .LBB0_330
	s_waitcnt vmcnt(8)
	v_mov_b64_e32 v[38:39], v[30:31]
	v_mov_b64_e32 v[34:35], v[26:27]
	v_mov_b64_e32 v[36:37], v[28:29]
	v_mov_b64_e32 v[32:33], v[24:25]
	s_mov_b32 s26, s25
	s_branch .LBB0_319
